# v44 with the stagger roles swapped (waves 0-3 take the mid-step barrier, waves 4-7 the tile-top barrier)
# baseline (speedup 1.0000x reference)
; template <int DQK, int MODE, int LDQ, int LDK, int LDV> ...
;     ...
;     float l_reg = 0.f; f32x16 o[4];
; #pragma unroll
;     for (int d = 0; d < 4; ++d)
; #pragma unroll
;         for (int r = 0; r < 16; ++r) o[d][r] = 0.f;
;     int kgo[NKP], vgo[2];
; #pragma unroll
;     for (int i = 0; i < NKP; ++i) { const int L = (wid + 8 * i) * 64 + lane, row = L / CPR, slot = L % CPR, cc = (slot & ~7) | ((slot & 7) ^ ((row >> 1) & 7)); kgo[i] = row * LDK + cc * 8; }
; #pragma unroll
;     for (int i = 0; i < 2; ++i) { const int L = (2 * wid + i) * 64 + lane, st = L >> 5, w5 = L & 31, kk = (st >> 2) * 8 + (w5 >> 2), c = (st & 3) * 32 + (w5 & 3) * 8;
;         const int k = (kk & ~0xC) | ((kk & 4) << 1) | ((kk & 8) >> 1); vgo[i] = k * LDV + c; }
;     ...
;     ATT_DMA_K(0); ATT_DMA_K(1); ATT_DMA_V(0, 0); ATT_DMA_K(2); ATT_DMA_V(1, 1);
;     bf16x8 qr[ND0];
;     { const bf16_t* Qw = Qb + (size_t)(wid * 32 + r32) * LDQ + hi * 8;
; #pragma unroll
;       for (int d0 = 0; d0 < ND0; ++d0) qr[d0] = *(const bf16x8*)(Qw + d0 * 16);
;       if constexpr (MODE == 0) {
;           float ss = 0.f;
; #pragma unroll
;           for (int d0 = 0; d0 < ND0; ++d0)
; #pragma unroll
;               for (int j = 0; j < 8; ++j) { const float f = bf2f((unsigned short)qr[d0][j]); ss += f * f; }
;           ss = swap_sum(ss);
;           const float rstd = rsqrtf(ss * (1.f / DQK) + EPS) * C;
; #pragma unroll
;           for (int d0 = 0; d0 < ND0; ++d0) { const float* g = gq + d0 * 16 + hi * 8;
;               { float f[8]; _Pragma("unroll") for (int j = 0; j < 8; ++j) f[j] = bf2f((unsigned short)qr[d0][j]) * rstd * g[j];
;                 u32x4 w = {cvtpk(f[0], f[1]), cvtpk(f[2], f[3]), cvtpk(f[4], f[5]), cvtpk(f[6], f[7])}; qr[d0] = __builtin_bit_cast(bf16x8, w); asm volatile("" ::: "memory"); } }
;       } }
;     const int qlo = q0 + wid * 32, qpos = qlo + r32;
;     const int tL = MODE == 0 ? 0 : (qlo >= 191 ? (qlo - 127) >> 6 : 0), tR = MODE == 0 ? NT : min(NT, (qlo + 222) >> 6);
;     float fL = 1.f, fR = 1.f; if constexpr (MODE != 0) { fL = __builtin_amdgcn_exp2f(bt[0]); fR = __builtin_amdgcn_exp2f(-bt[448]); }
;     ...
;     const int vbase = (int)(unsigned)(size_t)lds + V_OFF + v_rd_base(lane);
;     ...
;     ATT_TOP(NKP + 2);
;     { bf16x8 kf[NDA]; k_reads<DQK, 0, NDA>(kf, lds, 0, r32, hi); ATT_LGKM0(); qk_mma<0, NDA>(pA, kf, qr);
.LBB0_1919:
	s_lshl_b32 s87, s86, 7
	s_and_b32 s54, s0, 0xffffffc0
	s_min_i32 s97, s58, 64
	s_and_b32 s92, s73, 0xf00
	s_cmp_gt_i32 s55, 0
	s_cselect_b64 s[4:5], -1, 0
	s_add_i32 s93, 0, 0x18000
	s_add_i32 s1, s92, s94
	s_add_u32 s90, s2, s84
	v_add_lshl_u32 v2, s1, v2, 2
	s_addc_u32 s91, s3, 0
	v_readlane_b32 s1, v255, 6
	s_add_u32 s2, s1, s90
	s_addc_u32 s3, s76, s91
	s_add_i32 s7, s7, s6
	v_lshl_add_u64 v[100:101], v[0:1], 1, s[2:3]
	v_add3_u32 v0, s7, v6, v4
	v_lshl_or_b32 v0, v0, 11, v3
	v_and_b32_e32 v7, 63, v7
	v_add_u32_e32 v0, v0, v5
	s_add_u32 s2, s77, s90
	v_exp_f32_e32 v112, v9
	v_lshlrev_b32_e32 v8, 3, v7
	v_lshlrev_b32_e32 v9, 4, v7
	v_lshlrev_b32_e32 v7, 1, v7
	v_ashrrev_i32_e32 v1, 31, v0
	s_addc_u32 s3, s78, s91
	v_exp_f32_e64 v113, -v10
	v_and_b32_e32 v7, 32, v7
	v_lshl_add_u64 v[102:103], v[0:1], 1, s[2:3]
	v_add_u32_e32 v0, 64, v0
	v_and_b32_e32 v9, 0xc0, v9
	v_and_or_b32 v7, v8, s66, v7
	v_sub_u32_e32 v2, v130, v2
	v_ashrrev_i32_e32 v1, 31, v0
	v_mov_b32_e32 v14, v131
	v_mov_b32_e32 v15, v131
	v_add3_u32 v106, v9, s93, v7
	v_add_u32_e32 v119, 0, v2
	v_lshl_add_u64 v[104:105], v[0:1], 1, s[2:3]
	v_mov_b32_e32 v0, v131
	v_mov_b32_e32 v1, v131
	v_mov_b32_e32 v2, v131
	v_mov_b32_e32 v3, v131
	v_mov_b32_e32 v4, v131
	v_mov_b32_e32 v5, v131
	v_mov_b32_e32 v6, v131
	v_mov_b32_e32 v7, v131
	v_mov_b32_e32 v8, v131
	v_mov_b32_e32 v9, v131
	v_mov_b32_e32 v10, v131
	v_mov_b32_e32 v11, v131
	v_mov_b32_e32 v12, v131
	v_mov_b32_e32 v13, v131
	v_mov_b64_e32 v[62:63], v[14:15]
	v_mov_b64_e32 v[46:47], v[14:15]
	v_mov_b64_e32 v[30:31], v[14:15]
	s_mov_b32 s0, 1
	s_mov_b32 s23, 0
	s_mov_b32 s96, 2
	s_sub_i32 s62, 0, s55
	s_sub_i32 s6, 0, s97
	v_mov_b32_e32 v120, 0
	s_movk_i32 s7, 0xc300
	s_movk_i32 s22, 0x6000
	v_mov_b64_e32 v[60:61], v[12:13]
	v_mov_b64_e32 v[58:59], v[10:11]
	v_mov_b64_e32 v[56:57], v[8:9]
	v_mov_b64_e32 v[54:55], v[6:7]
	v_mov_b64_e32 v[52:53], v[4:5]
	v_mov_b64_e32 v[50:51], v[2:3]
	v_mov_b64_e32 v[48:49], v[0:1]
	v_mov_b64_e32 v[44:45], v[12:13]
	v_mov_b64_e32 v[42:43], v[10:11]
	v_mov_b64_e32 v[40:41], v[8:9]
	v_mov_b64_e32 v[38:39], v[6:7]
	v_mov_b64_e32 v[36:37], v[4:5]
	v_mov_b64_e32 v[34:35], v[2:3]
	v_mov_b64_e32 v[32:33], v[0:1]
	v_mov_b64_e32 v[28:29], v[12:13]
	v_mov_b64_e32 v[26:27], v[10:11]
	v_mov_b64_e32 v[24:25], v[8:9]
	v_mov_b64_e32 v[22:23], v[6:7]
	v_mov_b64_e32 v[20:21], v[4:5]
	v_mov_b64_e32 v[18:19], v[2:3]
	v_mov_b64_e32 v[16:17], v[0:1]
	s_mov_b32 s64, 1
	s_cmp_ge_u32 s33, 0x100
	s_cbranch_scc1 .Lstg_d0_pre_9
	s_waitcnt vmcnt(3)
	s_barrier
.Lstg_d0_pre_9:
.LBB0_1920:
	s_and_b32 s1, s22, 0x6000
	s_add_i32 m0, s59, s1
	s_lshl_b32 s1, s96, 14
	s_cmp_ge_u32 s33, 0x100
	s_cbranch_scc0 .Lstg_d0_top_10
	s_waitcnt vmcnt(3)
	s_barrier

; DI void expsum(f32x16& p, float& l_reg, bf16x8& pa0, bf16x8& pa1) {
; #pragma unroll
;     for (int r = 0; r < 16; ++r) p[r] = __builtin_amdgcn_exp2f(p[r]);
;     float ps = 0.f;
; #pragma unroll
;     for (int r = 0; r < 16; ++r) ps += p[r];
;     l_reg += ps; asm volatile("" : "+v"(l_reg));
;     ...
;     ATT_PK4(p, 0, pa0); ATT_PK4(p, 8, pa1);
;     ...
; }
.LBB0_1924:
	s_add_i32 s3, s22, 0xffffc000
	s_and_b32 s3, s3, 0x6000
	v_add_u32_e32 v123, s3, v114
	v_add_u32_e32 v140, v123, v118
	v_add_u32_e32 v136, v123, v117
	v_add_u32_e32 v132, v123, v116
	v_add_u32_e32 v123, v123, v115
	ds_read_b128 v[124:127], v123
	ds_read_b128 v[132:135], v132
	ds_read_b128 v[136:139], v136
	ds_read_b128 v[140:143], v140
	ds_read_b64_tr_b16 v[144:145], v121 offset:0x2000
	ds_read_b64_tr_b16 v[146:147], v121 offset:0x2800
	ds_read_b64_tr_b16 v[148:149], v121 offset:0x3000
	ds_read_b64_tr_b16 v[150:151], v121 offset:0x3800
	ds_read_b64_tr_b16 v[152:153], v121 offset:0x2200
	ds_read_b64_tr_b16 v[154:155], v121 offset:0x2a00
	ds_read_b64_tr_b16 v[156:157], v121 offset:0x3200
	ds_read_b64_tr_b16 v[158:159], v121 offset:0x3a00
	ds_read_b64_tr_b16 v[162:163], v121 offset:0x2400
	ds_read_b64_tr_b16 v[164:165], v121 offset:0x2c00
	ds_read_b64_tr_b16 v[166:167], v121 offset:0x3400
	ds_read_b64_tr_b16 v[168:169], v121 offset:0x3c00
	ds_read_b64_tr_b16 v[170:171], v121 offset:0x2600
	ds_read_b64_tr_b16 v[172:173], v121 offset:0x2e00
	ds_read_b64_tr_b16 v[174:175], v121 offset:0x3600
	ds_read_b64_tr_b16 v[176:177], v121 offset:0x3e00
	s_setprio 2
	v_exp_f32_e32 v64, v64
	v_exp_f32_e32 v65, v65
	v_exp_f32_e32 v66, v66
	v_exp_f32_e32 v67, v67
	v_exp_f32_e32 v68, v68
	v_add_f32_e32 v121, 0, v64
	v_exp_f32_e32 v69, v69
	v_add_f32_e32 v121, v65, v121
	v_exp_f32_e32 v70, v70
	v_add_f32_e32 v121, v66, v121
	v_exp_f32_e32 v71, v71
	v_add_f32_e32 v121, v67, v121
	v_exp_f32_e32 v72, v72
	v_add_f32_e32 v121, v68, v121
	v_exp_f32_e32 v73, v73
	v_add_f32_e32 v121, v69, v121
	v_exp_f32_e32 v74, v74
	v_add_f32_e32 v121, v70, v121
	v_exp_f32_e32 v75, v75
	v_add_f32_e32 v121, v71, v121
	v_exp_f32_e32 v76, v76
	v_add_f32_e32 v121, v72, v121
	v_exp_f32_e32 v77, v77
	v_add_f32_e32 v121, v73, v121
	v_exp_f32_e32 v78, v78
	v_add_f32_e32 v121, v74, v121
	v_exp_f32_e32 v79, v79
	v_add_f32_e32 v121, v75, v121
	v_add_f32_e32 v121, v76, v121
	v_add_f32_e32 v121, v77, v121
	v_add_f32_e32 v121, v78, v121
	v_add_f32_e32 v121, v79, v121
	v_add_f32_e32 v120, v120, v121
	v_cvt_pk_bf16_f32 v64, v64, v65
	v_cvt_pk_bf16_f32 v65, v66, v67
	v_cvt_pk_bf16_f32 v66, v68, v69
	v_cvt_pk_bf16_f32 v67, v70, v71
	v_cvt_pk_bf16_f32 v68, v72, v73
	v_cvt_pk_bf16_f32 v69, v74, v75
	v_cvt_pk_bf16_f32 v70, v76, v77
	v_cvt_pk_bf16_f32 v71, v78, v79
	s_nop 0
	v_permlane32_swap_b32_e32 v64, v66
	v_permlane32_swap_b32_e32 v65, v67
	v_permlane32_swap_b32_e32 v68, v70
	v_permlane32_swap_b32_e32 v69, v71
	s_waitcnt lgkmcnt(0)
	s_setprio 1
	s_cmp_ge_u32 s33, 0x100
	s_cbranch_scc1 .Lstg_d0_mid_11
	s_waitcnt vmcnt(3)
	s_barrier

; #define SBAR() __builtin_amdgcn_sched_barrier(0)
; #define ATT_DMA_K(t) do { const bf16_t* kg_ = Kh + (size_t)(t) * 64 * LDK; LAS unsigned char* sb_ = lds + ((t) & 3) * KBUF; \
;     _Pragma("unroll") for (int i_ = 0; i_ < NKP; ++i_) __builtin_amdgcn_global_load_lds((const unsigned*)(kg_ + kgo[i_]), (LAS unsigned*)(sb_ + (wid + 8 * i_) * 1024), 16, 0, 0); } while (0)
; #define ATT_DMA_V(t, vs) do { const bf16_t* vg_ = Vh + (size_t)(t) * 64 * LDV; LAS unsigned char* sb_ = lds + V_OFF + (vs) * SHM_V; \
;     _Pragma("unroll") for (int i_ = 0; i_ < 2; ++i_) __builtin_amdgcn_global_load_lds((const unsigned*)(vg_ + vgo[i_]), (LAS unsigned*)(sb_ + (2 * wid + i_) * 1024), 16, 0, 0); } while (0)
; #define ATT_SEG(t) do { if constexpr (MODE != 0) { if (((t) == tL && tL > 0) || (t) == tR) { const float f_ = (t) == tR ? fR : fL; l_reg *= f_; \
;     _Pragma("unroll") for (int d = 0; d < 4; ++d) _Pragma("unroll") for (int r = 0; r < 16; ++r) o[d][r] *= f_; } } } while (0)
; #define ATT_TOP(N) do { asm volatile("s_waitcnt vmcnt(%0)" :: "n"(N) : "memory"); __builtin_amdgcn_s_barrier(); asm volatile("" ::: "memory"); } while (0)
; template <int DQK, int MODE, int LDQ, int LDK, int LDV> ...
;     ...
;     for (int j = 0; j < NT; ++j) {
;         if (j + 2 < NT) ATT_TOP(NKP + 2); else ATT_TOP(0);
;         if (j + 3 < NT) ATT_DMA_K(j + 3);
;         if (j + 2 < NT) ATT_DMA_V(j + 2, v2);
;         ATT_SEG(j); SBAR();
.LBB0_1928:
	s_add_i32 s0, s95, s2
	s_add_i32 s1, s0, 0x400
	s_add_u32 s56, s56, 0xfc0000
	s_addc_u32 s57, s57, 0
	s_cmp_ge_u32 s33, 0x100
	s_cbranch_scc0 .Lstg_d0_t61_12
	s_waitcnt vmcnt(3)
	s_barrier

; DI void expsum(f32x16& p, float& l_reg, bf16x8& pa0, bf16x8& pa1) {
; #pragma unroll
;     for (int r = 0; r < 16; ++r) p[r] = __builtin_amdgcn_exp2f(p[r]);
;     float ps = 0.f;
; #pragma unroll
;     for (int r = 0; r < 16; ++r) ps += p[r];
;     l_reg += ps; asm volatile("" : "+v"(l_reg));
;     ...
;     ATT_PK4(p, 0, pa0); ATT_PK4(p, 8, pa1);
;     ...
; }
.LBB0_1932:
	s_movk_i32 s64, 0x70
	ds_read_b128 v[98:101], v107 offset:16384
	ds_read_b128 v[102:105], v108 offset:16384
	ds_read_b128 v[114:117], v109 offset:16384
	ds_read_b128 v[118:121], v110 offset:16384
	ds_read_b64_tr_b16 v[122:123], v96 offset:0x2000
	ds_read_b64_tr_b16 v[124:125], v96 offset:0x2800
	ds_read_b64_tr_b16 v[132:133], v96 offset:0x3000
	ds_read_b64_tr_b16 v[134:135], v96 offset:0x3800
	ds_read_b64_tr_b16 v[136:137], v96 offset:0x2200
	ds_read_b64_tr_b16 v[138:139], v96 offset:0x2a00
	ds_read_b64_tr_b16 v[140:141], v96 offset:0x3200
	ds_read_b64_tr_b16 v[142:143], v96 offset:0x3a00
	ds_read_b64_tr_b16 v[144:145], v96 offset:0x2400
	ds_read_b64_tr_b16 v[146:147], v96 offset:0x2c00
	ds_read_b64_tr_b16 v[148:149], v96 offset:0x3400
	ds_read_b64_tr_b16 v[150:151], v96 offset:0x3c00
	ds_read_b64_tr_b16 v[152:153], v96 offset:0x2600
	ds_read_b64_tr_b16 v[154:155], v96 offset:0x2e00
	ds_read_b64_tr_b16 v[156:157], v96 offset:0x3600
	ds_read_b64_tr_b16 v[158:159], v96 offset:0x3e00
	s_nop 5
	s_setprio 2
	v_exp_f32_e32 v64, v64
	v_exp_f32_e32 v65, v65
	v_exp_f32_e32 v66, v66
	v_exp_f32_e32 v67, v67
	v_exp_f32_e32 v68, v68
	v_add_f32_e32 v96, 0, v64
	v_exp_f32_e32 v69, v69
	v_add_f32_e32 v96, v65, v96
	v_exp_f32_e32 v70, v70
	v_add_f32_e32 v96, v66, v96
	v_exp_f32_e32 v71, v71
	v_add_f32_e32 v96, v67, v96
	v_exp_f32_e32 v72, v72
	v_add_f32_e32 v96, v68, v96
	v_exp_f32_e32 v73, v73
	v_add_f32_e32 v96, v69, v96
	v_exp_f32_e32 v74, v74
	v_add_f32_e32 v96, v70, v96
	v_exp_f32_e32 v75, v75
	v_add_f32_e32 v96, v71, v96
	v_exp_f32_e32 v76, v76
	v_add_f32_e32 v96, v72, v96
	v_exp_f32_e32 v77, v77
	v_add_f32_e32 v96, v73, v96
	v_exp_f32_e32 v78, v78
	v_add_f32_e32 v96, v74, v96
	v_exp_f32_e32 v79, v79
	v_add_f32_e32 v96, v75, v96
	v_add_f32_e32 v96, v76, v96
	v_add_f32_e32 v96, v77, v96
	v_add_f32_e32 v96, v78, v96
	v_add_f32_e32 v96, v79, v96
	v_add_f32_e32 v96, v97, v96
	v_cvt_pk_bf16_f32 v64, v64, v65
	v_cvt_pk_bf16_f32 v65, v66, v67
	v_cvt_pk_bf16_f32 v66, v68, v69
	v_cvt_pk_bf16_f32 v67, v70, v71
	v_cvt_pk_bf16_f32 v68, v72, v73
	v_cvt_pk_bf16_f32 v69, v74, v75
	v_cvt_pk_bf16_f32 v70, v76, v77
	v_cvt_pk_bf16_f32 v71, v78, v79
	s_nop 0
	v_permlane32_swap_b32_e32 v64, v66
	v_permlane32_swap_b32_e32 v65, v67
	v_permlane32_swap_b32_e32 v68, v70
	v_permlane32_swap_b32_e32 v69, v71
	s_waitcnt lgkmcnt(0)
	s_setprio 1
	s_cmp_ge_u32 s33, 0x100
	s_cbranch_scc1 .Lstg_d0_m61_13
	s_waitcnt vmcnt(0)
	s_barrier

; #define SBAR() __builtin_amdgcn_sched_barrier(0)
; #define ATT_DMA_K(t) do { const bf16_t* kg_ = Kh + (size_t)(t) * 64 * LDK; LAS unsigned char* sb_ = lds + ((t) & 3) * KBUF; \
;     _Pragma("unroll") for (int i_ = 0; i_ < NKP; ++i_) __builtin_amdgcn_global_load_lds((const unsigned*)(kg_ + kgo[i_]), (LAS unsigned*)(sb_ + (wid + 8 * i_) * 1024), 16, 0, 0); } while (0)
; #define ATT_DMA_V(t, vs) do { const bf16_t* vg_ = Vh + (size_t)(t) * 64 * LDV; LAS unsigned char* sb_ = lds + V_OFF + (vs) * SHM_V; \
;     _Pragma("unroll") for (int i_ = 0; i_ < 2; ++i_) __builtin_amdgcn_global_load_lds((const unsigned*)(vg_ + vgo[i_]), (LAS unsigned*)(sb_ + (2 * wid + i_) * 1024), 16, 0, 0); } while (0)
; #define ATT_SEG(t) do { if constexpr (MODE != 0) { if (((t) == tL && tL > 0) || (t) == tR) { const float f_ = (t) == tR ? fR : fL; l_reg *= f_; \
;     _Pragma("unroll") for (int d = 0; d < 4; ++d) _Pragma("unroll") for (int r = 0; r < 16; ++r) o[d][r] *= f_; } } } while (0)
; #define ATT_TOP(N) do { asm volatile("s_waitcnt vmcnt(%0)" :: "n"(N) : "memory"); __builtin_amdgcn_s_barrier(); asm volatile("" ::: "memory"); } while (0)
; template <int DQK, int MODE, int LDQ, int LDK, int LDV> ...
;     ...
;     for (int j = 0; j < NT; ++j) {
;         if (j + 2 < NT) ATT_TOP(NKP + 2); else ATT_TOP(0);
;         if (j + 3 < NT) ATT_DMA_K(j + 3);
;         if (j + 2 < NT) ATT_DMA_V(j + 2, v2);
;         ATT_SEG(j); SBAR();
.LBB0_1934:
	s_cmp_lg_u32 s55, 62
	s_cselect_b64 s[0:1], -1, 0
	s_cmp_eq_u32 s58, 62
	s_cselect_b64 s[4:5], -1, 0
	s_cmp_ge_u32 s33, 0x100
	s_cbranch_scc0 .Lstg_d0_t62_14
	s_waitcnt vmcnt(0)
	s_barrier

; DI void expsum(f32x16& p, float& l_reg, bf16x8& pa0, bf16x8& pa1) {
; #pragma unroll
;     for (int r = 0; r < 16; ++r) p[r] = __builtin_amdgcn_exp2f(p[r]);
;     float ps = 0.f;
; #pragma unroll
;     for (int r = 0; r < 16; ++r) ps += p[r];
;     l_reg += ps; asm volatile("" : "+v"(l_reg));
;     ...
;     ATT_PK4(p, 0, pa0); ATT_PK4(p, 8, pa1);
;     ...
; }
.LBB0_1938:
	ds_read_b128 v[100:103], v107 offset:24576
	ds_read_b128 v[114:117], v108 offset:24576
	ds_read_b128 v[118:121], v109 offset:24576
	ds_read_b128 v[122:125], v110 offset:24576
	ds_read_b64_tr_b16 v[132:133], v98 offset:0x2000
	ds_read_b64_tr_b16 v[134:135], v98 offset:0x2800
	ds_read_b64_tr_b16 v[136:137], v98 offset:0x3000
	ds_read_b64_tr_b16 v[138:139], v98 offset:0x3800
	ds_read_b64_tr_b16 v[140:141], v98 offset:0x2200
	ds_read_b64_tr_b16 v[142:143], v98 offset:0x2a00
	ds_read_b64_tr_b16 v[144:145], v98 offset:0x3200
	ds_read_b64_tr_b16 v[146:147], v98 offset:0x3a00
	ds_read_b64_tr_b16 v[148:149], v98 offset:0x2400
	ds_read_b64_tr_b16 v[150:151], v98 offset:0x2c00
	ds_read_b64_tr_b16 v[152:153], v98 offset:0x3400
	ds_read_b64_tr_b16 v[154:155], v98 offset:0x3c00
	ds_read_b64_tr_b16 v[156:157], v98 offset:0x2600
	ds_read_b64_tr_b16 v[158:159], v98 offset:0x2e00
	ds_read_b64_tr_b16 v[162:163], v98 offset:0x3600
	ds_read_b64_tr_b16 v[164:165], v98 offset:0x3e00
	s_nop 6
	s_setprio 2
	v_exp_f32_e32 v64, v64
	v_exp_f32_e32 v65, v65
	v_exp_f32_e32 v66, v66
	v_exp_f32_e32 v67, v67
	v_exp_f32_e32 v68, v68
	v_add_f32_e32 v97, 0, v64
	v_exp_f32_e32 v69, v69
	v_add_f32_e32 v97, v65, v97
	v_exp_f32_e32 v70, v70
	v_add_f32_e32 v97, v66, v97
	v_exp_f32_e32 v71, v71
	v_add_f32_e32 v97, v67, v97
	v_exp_f32_e32 v72, v72
	v_add_f32_e32 v97, v68, v97
	v_exp_f32_e32 v73, v73
	v_add_f32_e32 v97, v69, v97
	v_exp_f32_e32 v74, v74
	v_add_f32_e32 v97, v70, v97
	v_exp_f32_e32 v75, v75
	v_add_f32_e32 v97, v71, v97
	v_exp_f32_e32 v76, v76
	v_add_f32_e32 v97, v72, v97
	v_exp_f32_e32 v77, v77
	v_add_f32_e32 v97, v73, v97
	v_exp_f32_e32 v78, v78
	v_add_f32_e32 v97, v74, v97
	v_exp_f32_e32 v79, v79
	v_add_f32_e32 v97, v75, v97
	v_add_f32_e32 v97, v76, v97
	v_add_f32_e32 v97, v77, v97
	v_add_f32_e32 v97, v78, v97
	v_add_f32_e32 v97, v79, v97
	v_add_f32_e32 v96, v96, v97
	v_cvt_pk_bf16_f32 v64, v64, v65
	v_cvt_pk_bf16_f32 v65, v66, v67
	v_cvt_pk_bf16_f32 v66, v68, v69
	v_cvt_pk_bf16_f32 v67, v70, v71
	v_cvt_pk_bf16_f32 v68, v72, v73
	v_cvt_pk_bf16_f32 v69, v74, v75
	v_cvt_pk_bf16_f32 v70, v76, v77
	v_cvt_pk_bf16_f32 v71, v78, v79
	s_nop 0
	v_permlane32_swap_b32_e32 v64, v66
	v_permlane32_swap_b32_e32 v65, v67
	v_permlane32_swap_b32_e32 v68, v70
	v_permlane32_swap_b32_e32 v69, v71
	s_waitcnt lgkmcnt(0)
	s_setprio 1
	s_cmp_ge_u32 s33, 0x100
	s_cbranch_scc1 .Lstg_d0_m62_15
	s_waitcnt vmcnt(0)
	s_barrier

; #define SBAR() __builtin_amdgcn_sched_barrier(0)
; #define ATT_DMA_K(t) do { const bf16_t* kg_ = Kh + (size_t)(t) * 64 * LDK; LAS unsigned char* sb_ = lds + ((t) & 3) * KBUF; \
;     _Pragma("unroll") for (int i_ = 0; i_ < NKP; ++i_) __builtin_amdgcn_global_load_lds((const unsigned*)(kg_ + kgo[i_]), (LAS unsigned*)(sb_ + (wid + 8 * i_) * 1024), 16, 0, 0); } while (0)
; #define ATT_DMA_V(t, vs) do { const bf16_t* vg_ = Vh + (size_t)(t) * 64 * LDV; LAS unsigned char* sb_ = lds + V_OFF + (vs) * SHM_V; \
;     _Pragma("unroll") for (int i_ = 0; i_ < 2; ++i_) __builtin_amdgcn_global_load_lds((const unsigned*)(vg_ + vgo[i_]), (LAS unsigned*)(sb_ + (2 * wid + i_) * 1024), 16, 0, 0); } while (0)
; #define ATT_SEG(t) do { if constexpr (MODE != 0) { if (((t) == tL && tL > 0) || (t) == tR) { const float f_ = (t) == tR ? fR : fL; l_reg *= f_; \
;     _Pragma("unroll") for (int d = 0; d < 4; ++d) _Pragma("unroll") for (int r = 0; r < 16; ++r) o[d][r] *= f_; } } } while (0)
; #define ATT_TOP(N) do { asm volatile("s_waitcnt vmcnt(%0)" :: "n"(N) : "memory"); __builtin_amdgcn_s_barrier(); asm volatile("" ::: "memory"); } while (0)
; template <int DQK, int MODE, int LDQ, int LDK, int LDV> ...
;     ...
;     for (int j = 0; j < NT; ++j) {
;         if (j + 2 < NT) ATT_TOP(NKP + 2); else ATT_TOP(0);
;         if (j + 3 < NT) ATT_DMA_K(j + 3);
;         if (j + 2 < NT) ATT_DMA_V(j + 2, v2);
;         ATT_SEG(j); SBAR();
.LBB0_1940:
	s_cmp_lg_u32 s55, 63
	s_cselect_b64 s[0:1], -1, 0
	s_cmp_eq_u32 s58, 63
	s_cselect_b64 s[4:5], -1, 0
	s_cmp_ge_u32 s33, 0x100
	s_cbranch_scc0 .Lstg_d0_t63_16
	s_waitcnt vmcnt(0)
	s_barrier

; template <int DQK, int MODE, int LDQ, int LDK, int LDV> ...
;     ...
;     float l_reg = 0.f; f32x16 o[4];
; #pragma unroll
;     for (int d = 0; d < 4; ++d)
; #pragma unroll
;         for (int r = 0; r < 16; ++r) o[d][r] = 0.f;
;     int kgo[NKP], vgo[2];
; #pragma unroll
;     for (int i = 0; i < NKP; ++i) { const int L = (wid + 8 * i) * 64 + lane, row = L / CPR, slot = L % CPR, cc = (slot & ~7) | ((slot & 7) ^ ((row >> 1) & 7)); kgo[i] = row * LDK + cc * 8; }
; #pragma unroll
;     for (int i = 0; i < 2; ++i) { const int L = (2 * wid + i) * 64 + lane, st = L >> 5, w5 = L & 31, kk = (st >> 2) * 8 + (w5 >> 2), c = (st & 3) * 32 + (w5 & 3) * 8;
;         const int k = (kk & ~0xC) | ((kk & 4) << 1) | ((kk & 8) >> 1); vgo[i] = k * LDV + c; }
;     ...
;     ATT_DMA_K(0); ATT_DMA_K(1); ATT_DMA_V(0, 0); ATT_DMA_K(2); ATT_DMA_V(1, 1);
;     bf16x8 qr[ND0];
;     { const bf16_t* Qw = Qb + (size_t)(wid * 32 + r32) * LDQ + hi * 8;
; #pragma unroll
;       for (int d0 = 0; d0 < ND0; ++d0) qr[d0] = *(const bf16x8*)(Qw + d0 * 16);
;       if constexpr (MODE == 0) {
;           float ss = 0.f;
; #pragma unroll
;           for (int d0 = 0; d0 < ND0; ++d0)
; #pragma unroll
;               for (int j = 0; j < 8; ++j) { const float f = bf2f((unsigned short)qr[d0][j]); ss += f * f; }
;           ss = swap_sum(ss);
;           const float rstd = rsqrtf(ss * (1.f / DQK) + EPS) * C;
; #pragma unroll
;           for (int d0 = 0; d0 < ND0; ++d0) { const float* g = gq + d0 * 16 + hi * 8;
;               { float f[8]; _Pragma("unroll") for (int j = 0; j < 8; ++j) f[j] = bf2f((unsigned short)qr[d0][j]) * rstd * g[j];
;                 u32x4 w = {cvtpk(f[0], f[1]), cvtpk(f[2], f[3]), cvtpk(f[4], f[5]), cvtpk(f[6], f[7])}; qr[d0] = __builtin_bit_cast(bf16x8, w); asm volatile("" ::: "memory"); } }
;       } }
;     const int qlo = q0 + wid * 32, qpos = qlo + r32;
;     const int tL = MODE == 0 ? 0 : (qlo >= 191 ? (qlo - 127) >> 6 : 0), tR = MODE == 0 ? NT : min(NT, (qlo + 222) >> 6);
;     float fL = 1.f, fR = 1.f; if constexpr (MODE != 0) { fL = __builtin_amdgcn_exp2f(bt[0]); fR = __builtin_amdgcn_exp2f(-bt[448]); }
;     ...
;     const int vbase = (int)(unsigned)(size_t)lds + V_OFF + v_rd_base(lane);
;     ...
;     ATT_TOP(NKP + 2);
;     { bf16x8 kf[NDA]; k_reads<DQK, 0, NDA>(kf, lds, 0, r32, hi); ATT_LGKM0(); qk_mma<0, NDA>(pA, kf, qr);
.LBB0_1950:
	s_and_b32 s44, s0, 0xffffffc0
	s_min_i32 s52, s45, 64
	s_cmp_gt_i32 s47, 0
	s_cselect_b64 s[4:5], -1, 0
	s_add_i32 s92, s92, s46
	s_add_u32 s6, s79, s90
	s_addc_u32 s7, s80, s91
	s_add_i32 s3, s3, s2
	v_lshl_add_u64 v[100:101], v[0:1], 1, s[6:7]
	v_add3_u32 v0, s3, v6, v4
	v_lshl_or_b32 v0, v0, 11, v3
	v_and_b32_e32 v7, 63, v7
	v_add_u32_e32 v0, v0, v5
	s_add_u32 s2, s77, s90
	v_exp_f32_e32 v112, v9
	v_lshlrev_b32_e32 v8, 3, v7
	v_lshlrev_b32_e32 v9, 4, v7
	v_lshlrev_b32_e32 v7, 1, v7
	v_ashrrev_i32_e32 v1, 31, v0
	s_addc_u32 s3, s78, s91
	v_exp_f32_e64 v113, -v10
	v_and_b32_e32 v7, 32, v7
	v_add_lshl_u32 v2, s92, v2, 2
	v_lshl_add_u64 v[102:103], v[0:1], 1, s[2:3]
	v_add_u32_e32 v0, 64, v0
	v_and_b32_e32 v9, 0xc0, v9
	v_and_or_b32 v7, v8, s66, v7
	v_sub_u32_e32 v2, v130, v2
	v_ashrrev_i32_e32 v1, 31, v0
	v_mov_b32_e32 v14, v131
	v_mov_b32_e32 v15, v131
	v_add3_u32 v106, v9, s93, v7
	v_add_u32_e32 v119, 0, v2
	v_lshl_add_u64 v[104:105], v[0:1], 1, s[2:3]
	v_mov_b32_e32 v0, v131
	v_mov_b32_e32 v1, v131
	v_mov_b32_e32 v2, v131
	v_mov_b32_e32 v3, v131
	v_mov_b32_e32 v4, v131
	v_mov_b32_e32 v5, v131
	v_mov_b32_e32 v6, v131
	v_mov_b32_e32 v7, v131
	v_mov_b32_e32 v8, v131
	v_mov_b32_e32 v9, v131
	v_mov_b32_e32 v10, v131
	v_mov_b32_e32 v11, v131
	v_mov_b32_e32 v12, v131
	v_mov_b32_e32 v13, v131
	v_mov_b64_e32 v[62:63], v[14:15]
	v_mov_b64_e32 v[30:31], v[14:15]
	v_mov_b64_e32 v[46:47], v[14:15]
	s_mov_b32 s0, 1
	s_mov_b32 s62, 0
	s_mov_b32 s1, 2
	s_sub_i32 s53, 0, s47
	s_sub_i32 s6, 0, s52
	v_mov_b32_e32 v120, 0
	s_movk_i32 s7, 0xc300
	s_movk_i32 s22, 0x6000
	v_mov_b64_e32 v[60:61], v[12:13]
	v_mov_b64_e32 v[58:59], v[10:11]
	v_mov_b64_e32 v[56:57], v[8:9]
	v_mov_b64_e32 v[54:55], v[6:7]
	v_mov_b64_e32 v[52:53], v[4:5]
	v_mov_b64_e32 v[50:51], v[2:3]
	v_mov_b64_e32 v[48:49], v[0:1]
	v_mov_b64_e32 v[28:29], v[12:13]
	v_mov_b64_e32 v[26:27], v[10:11]
	v_mov_b64_e32 v[24:25], v[8:9]
	v_mov_b64_e32 v[22:23], v[6:7]
	v_mov_b64_e32 v[20:21], v[4:5]
	v_mov_b64_e32 v[18:19], v[2:3]
	v_mov_b64_e32 v[16:17], v[0:1]
	v_mov_b64_e32 v[44:45], v[12:13]
	v_mov_b64_e32 v[42:43], v[10:11]
	v_mov_b64_e32 v[40:41], v[8:9]
	v_mov_b64_e32 v[38:39], v[6:7]
	v_mov_b64_e32 v[36:37], v[4:5]
	v_mov_b64_e32 v[34:35], v[2:3]
	v_mov_b64_e32 v[32:33], v[0:1]
	s_mov_b32 s49, 1
	s_cmp_ge_u32 s33, 0x100
	s_cbranch_scc1 .Lstg_d1_pre_17
	s_waitcnt vmcnt(3)
	s_barrier
.Lstg_d1_pre_17:
.LBB0_1951:
	s_and_b32 s2, s22, 0x6000
	s_add_i32 m0, s94, s2
	s_lshl_b32 s2, s1, 14
	s_cmp_ge_u32 s33, 0x100
	s_cbranch_scc0 .Lstg_d1_top_18
	s_waitcnt vmcnt(3)
	s_barrier

; #define SBAR() __builtin_amdgcn_sched_barrier(0)
; #define ATT_DMA_K(t) do { const bf16_t* kg_ = Kh + (size_t)(t) * 64 * LDK; LAS unsigned char* sb_ = lds + ((t) & 3) * KBUF; \
;     _Pragma("unroll") for (int i_ = 0; i_ < NKP; ++i_) __builtin_amdgcn_global_load_lds((const unsigned*)(kg_ + kgo[i_]), (LAS unsigned*)(sb_ + (wid + 8 * i_) * 1024), 16, 0, 0); } while (0)
; #define ATT_DMA_V(t, vs) do { const bf16_t* vg_ = Vh + (size_t)(t) * 64 * LDV; LAS unsigned char* sb_ = lds + V_OFF + (vs) * SHM_V; \
;     _Pragma("unroll") for (int i_ = 0; i_ < 2; ++i_) __builtin_amdgcn_global_load_lds((const unsigned*)(vg_ + vgo[i_]), (LAS unsigned*)(sb_ + (2 * wid + i_) * 1024), 16, 0, 0); } while (0)
; #define ATT_SEG(t) do { if constexpr (MODE != 0) { if (((t) == tL && tL > 0) || (t) == tR) { const float f_ = (t) == tR ? fR : fL; l_reg *= f_; \
;     _Pragma("unroll") for (int d = 0; d < 4; ++d) _Pragma("unroll") for (int r = 0; r < 16; ++r) o[d][r] *= f_; } } } while (0)
; #define ATT_TOP(N) do { asm volatile("s_waitcnt vmcnt(%0)" :: "n"(N) : "memory"); __builtin_amdgcn_s_barrier(); asm volatile("" ::: "memory"); } while (0)
; template <int DQK, int MODE, int LDQ, int LDK, int LDV> ...
;     ...
;     for (int j = 0; j < NT; ++j) {
;         if (j + 2 < NT) ATT_TOP(NKP + 2); else ATT_TOP(0);
;         if (j + 3 < NT) ATT_DMA_K(j + 3);
;         if (j + 2 < NT) ATT_DMA_V(j + 2, v2);
;         ATT_SEG(j); SBAR();
.LBB0_1959:
	s_add_i32 s0, s48, s2
	s_cmp_ge_u32 s33, 0x100
	s_cbranch_scc0 .Lstg_d1_t61_20
	s_waitcnt vmcnt(3)
	s_barrier

; DI void expsum(f32x16& p, float& l_reg, bf16x8& pa0, bf16x8& pa1) {
; #pragma unroll
;     for (int r = 0; r < 16; ++r) p[r] = __builtin_amdgcn_exp2f(p[r]);
;     float ps = 0.f;
; #pragma unroll
;     for (int r = 0; r < 16; ++r) ps += p[r];
;     l_reg += ps; asm volatile("" : "+v"(l_reg));
;     ...
;     ATT_PK4(p, 0, pa0); ATT_PK4(p, 8, pa1);
;     ...
; }
.LBB0_1963:
	ds_read_b128 v[98:101], v107 offset:16384
	ds_read_b128 v[102:105], v108 offset:16384
	ds_read_b128 v[114:117], v109 offset:16384
	ds_read_b128 v[118:121], v110 offset:16384
	ds_read_b64_tr_b16 v[122:123], v96 offset:0x2000
	ds_read_b64_tr_b16 v[124:125], v96 offset:0x2800
	ds_read_b64_tr_b16 v[132:133], v96 offset:0x3000
	ds_read_b64_tr_b16 v[134:135], v96 offset:0x3800
	ds_read_b64_tr_b16 v[136:137], v96 offset:0x2200
	ds_read_b64_tr_b16 v[138:139], v96 offset:0x2a00
	ds_read_b64_tr_b16 v[140:141], v96 offset:0x3200
	ds_read_b64_tr_b16 v[142:143], v96 offset:0x3a00
	ds_read_b64_tr_b16 v[144:145], v96 offset:0x2400
	ds_read_b64_tr_b16 v[146:147], v96 offset:0x2c00
	ds_read_b64_tr_b16 v[148:149], v96 offset:0x3400
	ds_read_b64_tr_b16 v[150:151], v96 offset:0x3c00
	ds_read_b64_tr_b16 v[152:153], v96 offset:0x2600
	ds_read_b64_tr_b16 v[154:155], v96 offset:0x2e00
	ds_read_b64_tr_b16 v[156:157], v96 offset:0x3600
	ds_read_b64_tr_b16 v[158:159], v96 offset:0x3e00
	s_nop 6
	s_setprio 2
	v_exp_f32_e32 v64, v64
	v_exp_f32_e32 v65, v65
	v_exp_f32_e32 v66, v66
	v_exp_f32_e32 v67, v67
	v_exp_f32_e32 v68, v68
	v_add_f32_e32 v96, 0, v64
	v_exp_f32_e32 v69, v69
	v_add_f32_e32 v96, v65, v96
	v_exp_f32_e32 v70, v70
	v_add_f32_e32 v96, v66, v96
	v_exp_f32_e32 v71, v71
	v_add_f32_e32 v96, v67, v96
	v_exp_f32_e32 v72, v72
	v_add_f32_e32 v96, v68, v96
	v_exp_f32_e32 v73, v73
	v_add_f32_e32 v96, v69, v96
	v_exp_f32_e32 v74, v74
	v_add_f32_e32 v96, v70, v96
	v_exp_f32_e32 v75, v75
	v_add_f32_e32 v96, v71, v96
	v_exp_f32_e32 v76, v76
	v_add_f32_e32 v96, v72, v96
	v_exp_f32_e32 v77, v77
	v_add_f32_e32 v96, v73, v96
	v_exp_f32_e32 v78, v78
	v_add_f32_e32 v96, v74, v96
	v_exp_f32_e32 v79, v79
	v_add_f32_e32 v96, v75, v96
	v_add_f32_e32 v96, v76, v96
	v_add_f32_e32 v96, v77, v96
	v_add_f32_e32 v96, v78, v96
	v_add_f32_e32 v96, v79, v96
	v_add_f32_e32 v96, v97, v96
	v_cvt_pk_bf16_f32 v64, v64, v65
	v_cvt_pk_bf16_f32 v65, v66, v67
	v_cvt_pk_bf16_f32 v66, v68, v69
	v_cvt_pk_bf16_f32 v67, v70, v71
	v_cvt_pk_bf16_f32 v68, v72, v73
	v_cvt_pk_bf16_f32 v69, v74, v75
	v_cvt_pk_bf16_f32 v70, v76, v77
	v_cvt_pk_bf16_f32 v71, v78, v79
	s_nop 0
	v_permlane32_swap_b32_e32 v64, v66
	v_permlane32_swap_b32_e32 v65, v67
	v_permlane32_swap_b32_e32 v68, v70
	v_permlane32_swap_b32_e32 v69, v71
	s_waitcnt lgkmcnt(0)
	s_setprio 1
	s_cmp_ge_u32 s33, 0x100
	s_cbranch_scc1 .Lstg_d1_m61_21
	s_waitcnt vmcnt(0)
	s_barrier

; #define SBAR() __builtin_amdgcn_sched_barrier(0)
; #define ATT_DMA_K(t) do { const bf16_t* kg_ = Kh + (size_t)(t) * 64 * LDK; LAS unsigned char* sb_ = lds + ((t) & 3) * KBUF; \
;     _Pragma("unroll") for (int i_ = 0; i_ < NKP; ++i_) __builtin_amdgcn_global_load_lds((const unsigned*)(kg_ + kgo[i_]), (LAS unsigned*)(sb_ + (wid + 8 * i_) * 1024), 16, 0, 0); } while (0)
; #define ATT_DMA_V(t, vs) do { const bf16_t* vg_ = Vh + (size_t)(t) * 64 * LDV; LAS unsigned char* sb_ = lds + V_OFF + (vs) * SHM_V; \
;     _Pragma("unroll") for (int i_ = 0; i_ < 2; ++i_) __builtin_amdgcn_global_load_lds((const unsigned*)(vg_ + vgo[i_]), (LAS unsigned*)(sb_ + (2 * wid + i_) * 1024), 16, 0, 0); } while (0)
; #define ATT_SEG(t) do { if constexpr (MODE != 0) { if (((t) == tL && tL > 0) || (t) == tR) { const float f_ = (t) == tR ? fR : fL; l_reg *= f_; \
;     _Pragma("unroll") for (int d = 0; d < 4; ++d) _Pragma("unroll") for (int r = 0; r < 16; ++r) o[d][r] *= f_; } } } while (0)
; #define ATT_TOP(N) do { asm volatile("s_waitcnt vmcnt(%0)" :: "n"(N) : "memory"); __builtin_amdgcn_s_barrier(); asm volatile("" ::: "memory"); } while (0)
; template <int DQK, int MODE, int LDQ, int LDK, int LDV> ...
;     ...
;     for (int j = 0; j < NT; ++j) {
;         if (j + 2 < NT) ATT_TOP(NKP + 2); else ATT_TOP(0);
;         if (j + 3 < NT) ATT_DMA_K(j + 3);
;         if (j + 2 < NT) ATT_DMA_V(j + 2, v2);
;         ATT_SEG(j); SBAR();
.LBB0_1965:
	s_cmp_lg_u32 s47, 62
	s_cselect_b64 s[0:1], -1, 0
	s_cmp_eq_u32 s45, 62
	s_cselect_b64 s[4:5], -1, 0
	s_cmp_ge_u32 s33, 0x100
	s_cbranch_scc0 .Lstg_d1_t62_22
	s_waitcnt vmcnt(0)
	s_barrier

; #define SBAR() __builtin_amdgcn_sched_barrier(0)
; #define ATT_DMA_K(t) do { const bf16_t* kg_ = Kh + (size_t)(t) * 64 * LDK; LAS unsigned char* sb_ = lds + ((t) & 3) * KBUF; \
;     _Pragma("unroll") for (int i_ = 0; i_ < NKP; ++i_) __builtin_amdgcn_global_load_lds((const unsigned*)(kg_ + kgo[i_]), (LAS unsigned*)(sb_ + (wid + 8 * i_) * 1024), 16, 0, 0); } while (0)
; #define ATT_DMA_V(t, vs) do { const bf16_t* vg_ = Vh + (size_t)(t) * 64 * LDV; LAS unsigned char* sb_ = lds + V_OFF + (vs) * SHM_V; \
;     _Pragma("unroll") for (int i_ = 0; i_ < 2; ++i_) __builtin_amdgcn_global_load_lds((const unsigned*)(vg_ + vgo[i_]), (LAS unsigned*)(sb_ + (2 * wid + i_) * 1024), 16, 0, 0); } while (0)
; #define ATT_SEG(t) do { if constexpr (MODE != 0) { if (((t) == tL && tL > 0) || (t) == tR) { const float f_ = (t) == tR ? fR : fL; l_reg *= f_; \
;     _Pragma("unroll") for (int d = 0; d < 4; ++d) _Pragma("unroll") for (int r = 0; r < 16; ++r) o[d][r] *= f_; } } } while (0)
; #define ATT_TOP(N) do { asm volatile("s_waitcnt vmcnt(%0)" :: "n"(N) : "memory"); __builtin_amdgcn_s_barrier(); asm volatile("" ::: "memory"); } while (0)
; template <int DQK, int MODE, int LDQ, int LDK, int LDV> ...
;     ...
;     for (int j = 0; j < NT; ++j) {
;         if (j + 2 < NT) ATT_TOP(NKP + 2); else ATT_TOP(0);
;         if (j + 3 < NT) ATT_DMA_K(j + 3);
;         if (j + 2 < NT) ATT_DMA_V(j + 2, v2);
;         ATT_SEG(j); SBAR();
.LBB0_1971:
	s_cmp_lg_u32 s47, 63
	s_cselect_b64 s[0:1], -1, 0
	s_cmp_eq_u32 s45, 63
	s_cselect_b64 s[4:5], -1, 0
	s_cmp_ge_u32 s33, 0x100
	s_cbranch_scc0 .Lstg_d1_t63_24
	s_waitcnt vmcnt(0)
	s_barrier

; template <int DQK, int MODE, int LDQ, int LDK, int LDV> ...
;     ...
;     float l_reg = 0.f; f32x16 o[4];
; #pragma unroll
;     for (int d = 0; d < 4; ++d)
; #pragma unroll
;         for (int r = 0; r < 16; ++r) o[d][r] = 0.f;
;     int kgo[NKP], vgo[2];
; #pragma unroll
;     for (int i = 0; i < NKP; ++i) { const int L = (wid + 8 * i) * 64 + lane, row = L / CPR, slot = L % CPR, cc = (slot & ~7) | ((slot & 7) ^ ((row >> 1) & 7)); kgo[i] = row * LDK + cc * 8; }
; #pragma unroll
;     for (int i = 0; i < 2; ++i) { const int L = (2 * wid + i) * 64 + lane, st = L >> 5, w5 = L & 31, kk = (st >> 2) * 8 + (w5 >> 2), c = (st & 3) * 32 + (w5 & 3) * 8;
;         const int k = (kk & ~0xC) | ((kk & 4) << 1) | ((kk & 8) >> 1); vgo[i] = k * LDV + c; }
;     ...
;     ATT_DMA_K(0); ATT_DMA_K(1); ATT_DMA_V(0, 0); ATT_DMA_K(2); ATT_DMA_V(1, 1);
;     bf16x8 qr[ND0];
;     { const bf16_t* Qw = Qb + (size_t)(wid * 32 + r32) * LDQ + hi * 8;
; #pragma unroll
;       for (int d0 = 0; d0 < ND0; ++d0) qr[d0] = *(const bf16x8*)(Qw + d0 * 16);
;       if constexpr (MODE == 0) {
;           float ss = 0.f;
; #pragma unroll
;           for (int d0 = 0; d0 < ND0; ++d0)
; #pragma unroll
;               for (int j = 0; j < 8; ++j) { const float f = bf2f((unsigned short)qr[d0][j]); ss += f * f; }
;           ss = swap_sum(ss);
;           const float rstd = rsqrtf(ss * (1.f / DQK) + EPS) * C;
; #pragma unroll
;           for (int d0 = 0; d0 < ND0; ++d0) { const float* g = gq + d0 * 16 + hi * 8;
;               { float f[8]; _Pragma("unroll") for (int j = 0; j < 8; ++j) f[j] = bf2f((unsigned short)qr[d0][j]) * rstd * g[j];
;                 u32x4 w = {cvtpk(f[0], f[1]), cvtpk(f[2], f[3]), cvtpk(f[4], f[5]), cvtpk(f[6], f[7])}; qr[d0] = __builtin_bit_cast(bf16x8, w); asm volatile("" ::: "memory"); } }
;       } }
;     const int qlo = q0 + wid * 32, qpos = qlo + r32;
;     const int tL = MODE == 0 ? 0 : (qlo >= 191 ? (qlo - 127) >> 6 : 0), tR = MODE == 0 ? NT : min(NT, (qlo + 222) >> 6);
;     float fL = 1.f, fR = 1.f; if constexpr (MODE != 0) { fL = __builtin_amdgcn_exp2f(bt[0]); fR = __builtin_amdgcn_exp2f(-bt[448]); }
;     ...
;     const int vbase = (int)(unsigned)(size_t)lds + V_OFF + v_rd_base(lane);
;     ...
;     ATT_TOP(NKP + 2);
;     { bf16x8 kf[NDA]; k_reads<DQK, 0, NDA>(kf, lds, 0, r32, hi); ATT_LGKM0(); qk_mma<0, NDA>(pA, kf, qr);
.LBB0_1981:
	v_and_b32_e32 v0, 63, v36
	v_lshlrev_b32_e32 v1, 3, v0
	v_lshlrev_b32_e32 v2, 4, v0
	v_lshlrev_b32_e32 v0, 1, v0
	v_and_b32_e32 v0, 32, v0
	s_lshl_b32 s42, s86, 7
	s_andn2_b32 s55, s55, 63
	v_and_b32_e32 v2, 0xc0, v2
	s_mulk_i32 s85, 0x180
	v_and_or_b32 v0, v1, s66, v0
	s_add_i32 s0, 0, 0x18000
	v_add3_u32 v130, v2, s0, v0
	s_add_u32 s0, s54, s85
	s_addc_u32 s1, s53, 0
	s_add_u32 s0, s0, 0x1e048000
	s_addc_u32 s1, s1, 0
	v_lshl_add_u64 v[136:137], v[28:29], 1, s[0:1]
	v_lshl_add_u64 v[138:139], v[30:31], 1, s[0:1]
	v_lshl_add_u64 v[140:141], v[32:33], 1, s[0:1]
	s_add_u32 s0, s4, s84
	s_addc_u32 s1, s5, 0
	s_add_u32 s0, s0, 0x24020000
	s_addc_u32 s1, s1, 0
	s_add_i32 s58, s58, s57
	v_add3_u32 v0, s58, v41, v39
	v_lshl_or_b32 v0, v0, 9, v38
	v_add_u32_e32 v0, v0, v40
	v_add_u32_e32 v2, 64, v0
	v_ashrrev_i32_e32 v3, 31, v2
	v_ashrrev_i32_e32 v1, 31, v0
	v_mov_b32_e32 v173, 0
	v_mul_u32_u24_e32 v159, 0x180, v37
	s_mov_b32 s43, 3
	s_mov_b32 s44, 1
	v_lshl_add_u64 v[142:143], v[2:3], 1, s[0:1]
	v_lshl_add_u64 v[144:145], v[0:1], 1, s[0:1]
	s_mov_b32 s5, 0
	s_mov_b32 s4, 2
	v_mov_b32_e32 v0, 0
	v_mov_b32_e32 v1, v173
	v_mov_b32_e32 v2, v173
	v_mov_b32_e32 v3, v173
	v_mov_b32_e32 v4, v173
	v_mov_b32_e32 v5, v173
	v_mov_b32_e32 v6, v173
	v_mov_b32_e32 v7, v173
	v_mov_b32_e32 v8, v173
	v_mov_b32_e32 v9, v173
	v_mov_b32_e32 v10, v173
	v_mov_b32_e32 v11, v173
	v_mov_b32_e32 v12, v173
	v_mov_b32_e32 v13, v173
	v_mov_b32_e32 v14, v173
	v_mov_b32_e32 v15, v173
	v_mov_b32_e32 v16, 0
	v_mov_b32_e32 v17, v173
	v_mov_b32_e32 v18, v173
	v_mov_b32_e32 v19, v173
	v_mov_b32_e32 v20, v173
	v_mov_b32_e32 v21, v173
	v_mov_b32_e32 v22, v173
	v_mov_b32_e32 v23, v173
	v_mov_b32_e32 v24, v173
	v_mov_b32_e32 v25, v173
	v_mov_b32_e32 v26, v173
	v_mov_b32_e32 v27, v173
	v_mov_b32_e32 v28, v173
	v_mov_b32_e32 v29, v173
	v_mov_b32_e32 v30, v173
	v_mov_b32_e32 v31, v173
	v_mov_b32_e32 v32, 0
	v_mov_b32_e32 v33, v173
	v_mov_b32_e32 v34, v173
	v_mov_b32_e32 v35, v173
	v_mov_b32_e32 v36, v173
	v_mov_b32_e32 v37, v173
	v_mov_b32_e32 v38, v173
	v_mov_b32_e32 v39, v173
	v_mov_b32_e32 v40, v173
	v_mov_b32_e32 v41, v173
	v_mov_b32_e32 v42, v173
	v_mov_b32_e32 v43, v173
	v_mov_b32_e32 v44, v173
	v_mov_b32_e32 v45, v173
	v_mov_b32_e32 v46, v173
	v_mov_b32_e32 v47, v173
	v_mov_b32_e32 v48, 0
	v_mov_b32_e32 v49, v173
	v_mov_b32_e32 v50, v173
	v_mov_b32_e32 v51, v173
	v_mov_b32_e32 v52, v173
	v_mov_b32_e32 v53, v173
	v_mov_b32_e32 v54, v173
	v_mov_b32_e32 v55, v173
	v_mov_b32_e32 v56, v173
	v_mov_b32_e32 v57, v173
	v_mov_b32_e32 v58, v173
	v_mov_b32_e32 v59, v173
	v_mov_b32_e32 v60, v173
	v_mov_b32_e32 v61, v173
	v_mov_b32_e32 v62, v173
	v_mov_b32_e32 v63, v173
	s_cmp_ge_u32 s33, 0x100
	s_cbranch_scc1 .Lstg_mla_pre_1
	s_waitcnt vmcnt(5)
	s_barrier
.Lstg_mla_pre_1:
.LBB0_1982:
	s_and_b32 s1, s43, 3
	s_mulk_i32 s1, 0x6000
	s_add_i32 s1, s49, s1
	s_cmp_ge_u32 s33, 0x100
	s_cbranch_scc0 .Lstg_mla_top_2
	s_waitcnt vmcnt(5)
	s_barrier
.Lstg_mla_top_2:
	s_setprio 0
	s_mov_b32 m0, s1
	s_mov_b32 s0, s5
	s_mov_b32 s5, s44
	s_mov_b32 s44, s4
	s_lshl_b32 s4, s4, 14
	global_load_lds_dwordx4 v136, s[34:35]
	s_add_i32 m0, s1, 0x2000
	s_add_i32 s4, s52, s4
	global_load_lds_dwordx4 v138, s[34:35]
	s_add_i32 m0, s1, 0x4000
	s_add_i32 s6, s4, 0x400
	global_load_lds_dwordx4 v140, s[34:35]
	s_mov_b32 m0, s4
	s_add_i32 s1, s43, -3
	global_load_lds_dwordx4 v144, s[34:35]
	s_mov_b32 m0, s6
	s_nop 0
	global_load_lds_dwordx4 v142, s[34:35]
	s_and_b32 s1, s1, 3
	s_mulk_i32 s1, 0x6000
	v_add_u32_e32 v246, s1, v158
	v_add_u32_e32 v174, v246, v151
	v_add_u32_e32 v178, v246, v149
	v_add_u32_e32 v182, v246, v148
	v_add_u32_e32 v186, v246, v147
	v_add_u32_e32 v190, v246, v146
	v_add_u32_e32 v194, v246, v150
	s_lshl_b32 s1, s0, 14
	ds_read_b128 v[174:177], v174 offset:12288
	ds_read_b128 v[178:181], v178 offset:12288
	ds_read_b128 v[182:185], v182 offset:12288
	ds_read_b128 v[186:189], v186 offset:12288
	ds_read_b128 v[190:193], v190 offset:12288
	ds_read_b128 v[194:197], v194 offset:12288
	v_add_u32_e32 v254, s1, v130
	ds_read_b64_tr_b16 v[198:199], v254 offset:0
	ds_read_b64_tr_b16 v[200:201], v254 offset:0x800
	ds_read_b64_tr_b16 v[202:203], v254 offset:0x1000
	ds_read_b64_tr_b16 v[204:205], v254 offset:0x1800
	ds_read_b64_tr_b16 v[206:207], v254 offset:0x200
	ds_read_b64_tr_b16 v[208:209], v254 offset:0xa00
	ds_read_b64_tr_b16 v[210:211], v254 offset:0x1200
	ds_read_b64_tr_b16 v[212:213], v254 offset:0x1a00
	ds_read_b64_tr_b16 v[214:215], v254 offset:0x400
	ds_read_b64_tr_b16 v[216:217], v254 offset:0xc00
	ds_read_b64_tr_b16 v[218:219], v254 offset:0x1400
	ds_read_b64_tr_b16 v[220:221], v254 offset:0x1c00
	ds_read_b64_tr_b16 v[222:223], v254 offset:0x600
	ds_read_b64_tr_b16 v[224:225], v254 offset:0xe00
	ds_read_b64_tr_b16 v[226:227], v254 offset:0x1600
	ds_read_b64_tr_b16 v[228:229], v254 offset:0x1e00
	s_setprio 2
	v_exp_f32_e32 v64, v64
	v_exp_f32_e32 v65, v65
	v_exp_f32_e32 v66, v66
	v_exp_f32_e32 v67, v67
	v_exp_f32_e32 v68, v68
	v_add_f32_e32 v230, 0, v64
	v_exp_f32_e32 v69, v69
	v_add_f32_e32 v230, v65, v230
	v_exp_f32_e32 v70, v70
	v_add_f32_e32 v230, v66, v230
	v_exp_f32_e32 v71, v71
	v_add_f32_e32 v230, v67, v230
	v_exp_f32_e32 v72, v72
	v_add_f32_e32 v230, v68, v230
	v_exp_f32_e32 v73, v73
	v_add_f32_e32 v230, v69, v230
	v_exp_f32_e32 v74, v74
	v_add_f32_e32 v230, v70, v230
	v_exp_f32_e32 v75, v75
	v_add_f32_e32 v230, v71, v230
	v_exp_f32_e32 v76, v76
	v_add_f32_e32 v230, v72, v230
	v_exp_f32_e32 v77, v77
	v_add_f32_e32 v230, v73, v230
	v_exp_f32_e32 v78, v78
	v_add_f32_e32 v230, v74, v230
	v_exp_f32_e32 v79, v79
	v_add_f32_e32 v230, v75, v230
	v_add_f32_e32 v230, v76, v230
	v_add_f32_e32 v230, v77, v230
	v_add_f32_e32 v230, v78, v230
	v_add_f32_e32 v230, v79, v230
	v_add_f32_e32 v173, v173, v230
	v_cvt_pk_bf16_f32 v64, v64, v65
	v_cvt_pk_bf16_f32 v65, v66, v67
	v_cvt_pk_bf16_f32 v66, v68, v69
	v_cvt_pk_bf16_f32 v67, v70, v71
	v_cvt_pk_bf16_f32 v68, v72, v73
	v_cvt_pk_bf16_f32 v69, v74, v75
	v_cvt_pk_bf16_f32 v70, v76, v77
	v_cvt_pk_bf16_f32 v71, v78, v79
	s_nop 0
	v_permlane32_swap_b32_e32 v64, v66
	v_permlane32_swap_b32_e32 v65, v67
	v_permlane32_swap_b32_e32 v68, v70
	v_permlane32_swap_b32_e32 v69, v71
	s_waitcnt lgkmcnt(0)
; #define LAS __attribute__((address_space(3)))
; DI void expsum(f32x16& p, float& l_reg, bf16x8& pa0, bf16x8& pa1) {
; #pragma unroll
;     for (int r = 0; r < 16; ++r) p[r] = __builtin_amdgcn_exp2f(p[r]);
;     float ps = 0.f;
; #pragma unroll
;     for (int r = 0; r < 16; ++r) ps += p[r];
;     l_reg += ps; asm volatile("" : "+v"(l_reg));
;     ...
;     ATT_PK4(p, 0, pa0); ATT_PK4(p, 8, pa1);
;     ...
; }
; DI int v_rd_base(int lane) { return ((lane & 3) << 3) | (((lane >> 2) & 3) << 6) | (((lane >> 4) & 1) << 5) | (((lane >> 5) & 1) << 8); }
; template <int OFF> DI s16x4 tr_read(int vb) { s16x4 r; asm volatile("ds_read_b64_tr_b16 %0, %1 offset:%2" : "=&v"(r) : "v"(vb), "i"(OFF) : "memory"); return r; }
; template <int H> DI void v_reads(s16x4* vf, int vb) {
;     vf[0] = tr_read<v_rd_off(0, 2 * H, 0)>(vb); vf[1] = tr_read<v_rd_off(0, 2 * H, 1)>(vb); vf[2] = tr_read<v_rd_off(0, 2 * H + 1, 0)>(vb); vf[3] = tr_read<v_rd_off(0, 2 * H + 1, 1)>(vb);
;     vf[4] = tr_read<v_rd_off(1, 2 * H, 0)>(vb); vf[5] = tr_read<v_rd_off(1, 2 * H, 1)>(vb); vf[6] = tr_read<v_rd_off(1, 2 * H + 1, 0)>(vb); vf[7] = tr_read<v_rd_off(1, 2 * H + 1, 1)>(vb);
;     vf[8] = tr_read<v_rd_off(2, 2 * H, 0)>(vb); vf[9] = tr_read<v_rd_off(2, 2 * H, 1)>(vb); vf[10] = tr_read<v_rd_off(2, 2 * H + 1, 0)>(vb); vf[11] = tr_read<v_rd_off(2, 2 * H + 1, 1)>(vb);
;     vf[12] = tr_read<v_rd_off(3, 2 * H, 0)>(vb); vf[13] = tr_read<v_rd_off(3, 2 * H, 1)>(vb); vf[14] = tr_read<v_rd_off(3, 2 * H + 1, 0)>(vb); vf[15] = tr_read<v_rd_off(3, 2 * H + 1, 1)>(vb);
; }
; DI void pv_mma(f32x16* o, const s16x4* vf, bf16x8 pa0, bf16x8 pa1) {
;     ...
; #pragma unroll
;     for (int d0 = 0; d0 < 4; ++d0) {
;         o[d0] = __builtin_amdgcn_mfma_f32_32x32x16_bf16(pa0, ATT_PK(vf[4 * d0], vf[4 * d0 + 1]), o[d0], 0, 0, 0);
;         o[d0] = __builtin_amdgcn_mfma_f32_32x32x16_bf16(pa1, ATT_PK(vf[4 * d0 + 2], vf[4 * d0 + 3]), o[d0], 0, 0, 0); }
;     ...
; }
; template <int DQK, int D0A, int D0B> DI void k_reads(bf16x8* kf, const LAS unsigned char* Ks, int half, int r32, int hi) {
; #pragma unroll
;     for (int d0 = D0A; d0 < D0B; ++d0) kf[d0 - D0A] = *(const LAS bf16x8*)(Ks + half * (32 * DQK * 2) + kswz<DQK>(r32, (d0 * 16 + hi * 8) * 2));
; }
; template <int D0A, int D0B> DI void qk_mma(f32x16& p, const bf16x8* kf, const bf16x8* qr) {
; #pragma unroll
;     for (int d0 = D0A; d0 < D0B; ++d0) {
	v_add_u32_e32 v72, v246, v152
	v_add_u32_e32 v73, v246, v153
	ds_read_b128 v[230:233], v72 offset:12288
	ds_read_b128 v[234:237], v73 offset:12288
	v_add_u32_e32 v72, v246, v154
	v_add_u32_e32 v73, v246, v155
	ds_read_b128 v[238:241], v72 offset:12288
	ds_read_b128 v[242:245], v73 offset:12288
	v_add_u32_e32 v72, v246, v156
	v_add_u32_e32 v73, v246, v157
	ds_read_b128 v[246:249], v72 offset:12288
	ds_read_b128 v[250:253], v73 offset:12288
	s_setprio 1
	v_mfma_f32_32x32x16_bf16 v[48:63], v[64:67], v[198:201], v[48:63]
	v_mfma_f32_32x32x16_bf16 v[32:47], v[64:67], v[206:209], v[32:47]
	v_mfma_f32_32x32x16_bf16 v[16:31], v[64:67], v[214:217], v[16:31]
	v_mfma_f32_32x32x16_bf16 v[0:15], v[64:67], v[222:225], v[0:15]
	v_mfma_f32_32x32x16_bf16 v[48:63], v[68:71], v[202:205], v[48:63]
	v_mfma_f32_32x32x16_bf16 v[32:47], v[68:71], v[210:213], v[32:47]
	v_mfma_f32_32x32x16_bf16 v[16:31], v[68:71], v[218:221], v[16:31]
	v_mfma_f32_32x32x16_bf16 v[0:15], v[68:71], v[226:229], v[0:15]
	s_waitcnt lgkmcnt(0)
	v_mfma_f32_32x32x16_bf16 v[64:79], v[174:177], v[80:83], 0
	v_mfma_f32_32x32x16_bf16 v[64:79], v[178:181], v[84:87], v[64:79]
	v_mfma_f32_32x32x16_bf16 v[64:79], v[182:185], v[88:91], v[64:79]
	v_mfma_f32_32x32x16_bf16 v[64:79], v[186:189], v[92:95], v[64:79]
	v_mfma_f32_32x32x16_bf16 v[64:79], v[190:193], v[96:99], v[64:79]
	v_mfma_f32_32x32x16_bf16 v[64:79], v[194:197], v[100:103], v[64:79]
	v_mfma_f32_32x32x16_bf16 v[64:79], v[230:233], v[104:107], v[64:79]
	v_mfma_f32_32x32x16_bf16 v[64:79], v[234:237], v[108:111], v[64:79]
	v_mfma_f32_32x32x16_bf16 v[64:79], v[238:241], v[112:115], v[64:79]
	v_mfma_f32_32x32x16_bf16 v[64:79], v[242:245], v[116:119], v[64:79]
	v_mfma_f32_32x32x16_bf16 v[64:79], v[246:249], v[120:123], v[64:79]
	v_mfma_f32_32x32x16_bf16 v[64:79], v[250:253], v[124:127], v[64:79]
	s_setprio 0
	s_add_i32 s4, s43, -2
	s_and_b32 s4, s4, 3
	s_mulk_i32 s4, 0x6000
	v_add_u32_e32 v246, s4, v158
	v_add_u32_e32 v174, v246, v151
	v_add_u32_e32 v178, v246, v149
	v_add_u32_e32 v182, v246, v148
	v_add_u32_e32 v186, v246, v147
	v_add_u32_e32 v190, v246, v146
	v_add_u32_e32 v194, v246, v150
	ds_read_b128 v[174:177], v174
	ds_read_b128 v[178:181], v178
	ds_read_b128 v[182:185], v182
	ds_read_b128 v[186:189], v186
	ds_read_b128 v[190:193], v190
	ds_read_b128 v[194:197], v194
	ds_read_b64_tr_b16 v[198:199], v254 offset:0x2000
	ds_read_b64_tr_b16 v[200:201], v254 offset:0x2800
	ds_read_b64_tr_b16 v[202:203], v254 offset:0x3000
	ds_read_b64_tr_b16 v[204:205], v254 offset:0x3800
	ds_read_b64_tr_b16 v[206:207], v254 offset:0x2200
	ds_read_b64_tr_b16 v[208:209], v254 offset:0x2a00
	ds_read_b64_tr_b16 v[210:211], v254 offset:0x3200
	ds_read_b64_tr_b16 v[212:213], v254 offset:0x3a00
	ds_read_b64_tr_b16 v[214:215], v254 offset:0x2400
	ds_read_b64_tr_b16 v[216:217], v254 offset:0x2c00
	ds_read_b64_tr_b16 v[218:219], v254 offset:0x3400
	ds_read_b64_tr_b16 v[220:221], v254 offset:0x3c00
	ds_read_b64_tr_b16 v[222:223], v254 offset:0x2600
	ds_read_b64_tr_b16 v[224:225], v254 offset:0x2e00
	ds_read_b64_tr_b16 v[226:227], v254 offset:0x3600
	ds_read_b64_tr_b16 v[228:229], v254 offset:0x3e00
	s_setprio 2
	v_exp_f32_e32 v64, v64
	v_exp_f32_e32 v65, v65
	v_exp_f32_e32 v66, v66
	v_exp_f32_e32 v67, v67
	v_exp_f32_e32 v68, v68
	v_add_f32_e32 v230, 0, v64
	v_exp_f32_e32 v69, v69
	v_add_f32_e32 v230, v65, v230
	v_exp_f32_e32 v70, v70
	v_add_f32_e32 v230, v66, v230
	v_exp_f32_e32 v71, v71
	v_add_f32_e32 v230, v67, v230
	v_exp_f32_e32 v72, v72
	v_add_f32_e32 v230, v68, v230
	v_exp_f32_e32 v73, v73
	v_add_f32_e32 v230, v69, v230
	v_exp_f32_e32 v74, v74
	v_add_f32_e32 v230, v70, v230
	v_exp_f32_e32 v75, v75
	v_add_f32_e32 v230, v71, v230
	v_exp_f32_e32 v76, v76
	v_add_f32_e32 v230, v72, v230
	v_exp_f32_e32 v77, v77
	v_add_f32_e32 v230, v73, v230
	v_exp_f32_e32 v78, v78
	v_add_f32_e32 v230, v74, v230
	v_exp_f32_e32 v79, v79
	v_add_f32_e32 v230, v75, v230
	v_add_f32_e32 v230, v76, v230
	v_add_f32_e32 v230, v77, v230
	v_add_f32_e32 v230, v78, v230
	v_add_f32_e32 v230, v79, v230
	v_add_f32_e32 v173, v173, v230
	v_cvt_pk_bf16_f32 v64, v64, v65
	v_cvt_pk_bf16_f32 v65, v66, v67
	v_cvt_pk_bf16_f32 v66, v68, v69
	v_cvt_pk_bf16_f32 v67, v70, v71
	v_cvt_pk_bf16_f32 v68, v72, v73
	v_cvt_pk_bf16_f32 v69, v74, v75
	v_cvt_pk_bf16_f32 v70, v76, v77
	v_cvt_pk_bf16_f32 v71, v78, v79
	s_nop 0
	v_permlane32_swap_b32_e32 v64, v66
	v_permlane32_swap_b32_e32 v65, v67
	v_permlane32_swap_b32_e32 v68, v70
	v_permlane32_swap_b32_e32 v69, v71
	s_waitcnt lgkmcnt(0)
	v_add_u32_e32 v72, v246, v152
	v_add_u32_e32 v73, v246, v153
	ds_read_b128 v[230:233], v72
	ds_read_b128 v[234:237], v73
	v_add_u32_e32 v72, v246, v154
	v_add_u32_e32 v73, v246, v155
	ds_read_b128 v[238:241], v72
	ds_read_b128 v[242:245], v73
	v_add_u32_e32 v72, v246, v156
	v_add_u32_e32 v73, v246, v157
	ds_read_b128 v[246:249], v72
	ds_read_b128 v[250:253], v73
	s_setprio 1
	s_cmp_ge_u32 s33, 0x100
	s_cbranch_scc1 .Lstg_mla_mid_3
	s_waitcnt vmcnt(5)
	s_barrier
; #define LAS __attribute__((address_space(3)))
; #define SBAR() __builtin_amdgcn_sched_barrier(0)
; #define ATT_SEG(t) do { if constexpr (MODE != 0) { if (((t) == tL && tL > 0) || (t) == tR) { const float f_ = (t) == tR ? fR : fL; l_reg *= f_; \
;     _Pragma("unroll") for (int d = 0; d < 4; ++d) _Pragma("unroll") for (int r = 0; r < 16; ++r) o[d][r] *= f_; } } } while (0)
; DI void pv_mma(f32x16* o, const s16x4* vf, bf16x8 pa0, bf16x8 pa1) {
;     ...
; #pragma unroll
;     for (int d0 = 0; d0 < 4; ++d0) {
;         o[d0] = __builtin_amdgcn_mfma_f32_32x32x16_bf16(pa0, ATT_PK(vf[4 * d0], vf[4 * d0 + 1]), o[d0], 0, 0, 0);
;         o[d0] = __builtin_amdgcn_mfma_f32_32x32x16_bf16(pa1, ATT_PK(vf[4 * d0 + 2], vf[4 * d0 + 3]), o[d0], 0, 0, 0); }
;     ...
; }
; template <int DQK, int D0A, int D0B> DI void k_reads(bf16x8* kf, const LAS unsigned char* Ks, int half, int r32, int hi) {
; #pragma unroll
;     for (int d0 = D0A; d0 < D0B; ++d0) kf[d0 - D0A] = *(const LAS bf16x8*)(Ks + half * (32 * DQK * 2) + kswz<DQK>(r32, (d0 * 16 + hi * 8) * 2));
; }
; template <int D0A, int D0B> DI void qk_mma(f32x16& p, const bf16x8* kf, const bf16x8* qr) {
; #pragma unroll
;     for (int d0 = D0A; d0 < D0B; ++d0) {
;         if (d0 == 0) { f32x16 z; _Pragma("unroll") for (int r = 0; r < 16; ++r) z[r] = 0.f; p = __builtin_amdgcn_mfma_f32_32x32x16_bf16(kf[0], qr[0], z, 0, 0, 0); }
;         else p = __builtin_amdgcn_mfma_f32_32x32x16_bf16(kf[d0 - D0A], qr[d0], p, 0, 0, 0); }
; }
; template <int DQK, int MODE, int LDQ, int LDK, int LDV> ...
;     ...
;     constexpr int NDA = ND0 > 6 ? 6 : ND0;
;     ...
;     f32x16 pA, pB; bf16x8 pa0, pa1;
;     int v0 = 0, v1 = 1, v2 = 2;
;     ATT_TOP(NKP + 2);
;     { bf16x8 kf[NDA]; k_reads<DQK, 0, NDA>(kf, lds, 0, r32, hi); ATT_LGKM0(); qk_mma<0, NDA>(pA, kf, qr);
;       if constexpr (ND0 > NDA) { bf16x8 kg[ND0 - NDA]; k_reads<DQK, NDA, ND0>(kg, lds, 0, r32, hi); ATT_LGKM0(); qk_mma<NDA, ND0>(pA, kg, qr); }
;       ATT_BIAS(pA, 0, 0); }
;     if (wid >= 4) __builtin_amdgcn_s_setprio(1);
;     for (int j = 0; j < NT; ++j) {
;         if (j + 2 < NT) ATT_TOP(NKP + 2); else ATT_TOP(0);
;         if (j + 3 < NT) ATT_DMA_K(j + 3);
;         if (j + 2 < NT) ATT_DMA_V(j + 2, v2);
;         ATT_SEG(j); SBAR();
;         ATT_STEP(pA, pB, 0, v0, true, 1, j);
;         ATT_STEP(pB, pA, 1, v0, (j + 1 < NT), 0, j + 1);
;         { const int t_ = v0; v0 = v1; v1 = v2; v2 = t_; }
;     }
.Lstg_mla_mid_3:
	v_mfma_f32_32x32x16_bf16 v[48:63], v[64:67], v[198:201], v[48:63]
	v_mfma_f32_32x32x16_bf16 v[32:47], v[64:67], v[206:209], v[32:47]
	v_mfma_f32_32x32x16_bf16 v[16:31], v[64:67], v[214:217], v[16:31]
	v_mfma_f32_32x32x16_bf16 v[0:15], v[64:67], v[222:225], v[0:15]
	v_mfma_f32_32x32x16_bf16 v[48:63], v[68:71], v[202:205], v[48:63]
	v_mfma_f32_32x32x16_bf16 v[32:47], v[68:71], v[210:213], v[32:47]
	v_mfma_f32_32x32x16_bf16 v[16:31], v[68:71], v[218:221], v[16:31]
	v_mfma_f32_32x32x16_bf16 v[0:15], v[68:71], v[226:229], v[0:15]
	s_waitcnt lgkmcnt(0)
	v_mfma_f32_32x32x16_bf16 v[64:79], v[174:177], v[80:83], 0
	v_mfma_f32_32x32x16_bf16 v[64:79], v[178:181], v[84:87], v[64:79]
	v_mfma_f32_32x32x16_bf16 v[64:79], v[182:185], v[88:91], v[64:79]
	v_mfma_f32_32x32x16_bf16 v[64:79], v[186:189], v[92:95], v[64:79]
	v_mfma_f32_32x32x16_bf16 v[64:79], v[190:193], v[96:99], v[64:79]
	v_mfma_f32_32x32x16_bf16 v[64:79], v[194:197], v[100:103], v[64:79]
	v_mfma_f32_32x32x16_bf16 v[64:79], v[230:233], v[104:107], v[64:79]
	v_mfma_f32_32x32x16_bf16 v[64:79], v[234:237], v[108:111], v[64:79]
	v_mfma_f32_32x32x16_bf16 v[64:79], v[238:241], v[112:115], v[64:79]
	v_mfma_f32_32x32x16_bf16 v[64:79], v[242:245], v[116:119], v[64:79]
	v_mfma_f32_32x32x16_bf16 v[64:79], v[246:249], v[120:123], v[64:79]
	v_mfma_f32_32x32x16_bf16 v[64:79], v[250:253], v[124:127], v[64:79]
	s_add_i32 s43, s43, 1
	v_add_u32_e32 v136, s36, v136
	v_add_u32_e32 v138, s36, v138
	v_add_u32_e32 v140, s36, v140
	v_add_u32_e32 v142, s38, v142
	v_add_u32_e32 v144, s38, v144
	s_cmp_eq_u32 s43, 64
	s_mov_b32 s4, s0
	s_cbranch_scc0 .LBB0_1982
	s_lshl_b32 s0, s55, 2
	s_add_i32 s4, s0, 0
	s_add_i32 s6, s52, s1
	s_add_i32 s4, s4, 0x24000
	s_add_i32 s7, s6, 0x400
	s_add_u32 s0, s2, 0x3f0000
	s_addc_u32 s1, s3, 0
	s_cmp_ge_u32 s33, 0x100
	s_cbranch_scc0 .Lstg_mla_t61_4
	s_waitcnt vmcnt(5)
	s_barrier
.Lstg_mla_t61_4:
	s_setprio 0
	v_lshl_add_u64 v[132:133], v[132:133], 1, s[0:1]
	s_mov_b32 m0, s6
	v_lshl_add_u64 v[134:135], v[134:135], 1, s[0:1]
	global_load_lds_dwordx4 v[132:133], off
	s_mov_b32 m0, s7
	s_nop 0
	global_load_lds_dwordx4 v[134:135], off
	ds_read_b128 v[132:135], v161 offset:36864
	ds_read_b128 v[136:139], v162 offset:36864
	ds_read_b128 v[140:143], v163 offset:36864
	ds_read_b128 v[174:177], v164 offset:36864
	ds_read_b128 v[178:181], v165 offset:36864
	ds_read_b128 v[182:185], v166 offset:36864
	v_lshl_add_u32 v144, s5, 14, v130
	ds_read_b64_tr_b16 v[186:187], v144 offset:0
	ds_read_b64_tr_b16 v[188:189], v144 offset:0x800
	ds_read_b64_tr_b16 v[190:191], v144 offset:0x1000
	ds_read_b64_tr_b16 v[192:193], v144 offset:0x1800
	ds_read_b64_tr_b16 v[194:195], v144 offset:0x200
	ds_read_b64_tr_b16 v[196:197], v144 offset:0xa00
	ds_read_b64_tr_b16 v[198:199], v144 offset:0x1200
	ds_read_b64_tr_b16 v[200:201], v144 offset:0x1a00
	ds_read_b64_tr_b16 v[202:203], v144 offset:0x400
	ds_read_b64_tr_b16 v[204:205], v144 offset:0xc00
	ds_read_b64_tr_b16 v[206:207], v144 offset:0x1400
	ds_read_b64_tr_b16 v[208:209], v144 offset:0x1c00
	ds_read_b64_tr_b16 v[210:211], v144 offset:0x600
	ds_read_b64_tr_b16 v[212:213], v144 offset:0xe00
	ds_read_b64_tr_b16 v[214:215], v144 offset:0x1600
	ds_read_b64_tr_b16 v[216:217], v144 offset:0x1e00
	s_setprio 2
	v_exp_f32_e32 v64, v64
	v_exp_f32_e32 v65, v65
	v_exp_f32_e32 v66, v66
	v_exp_f32_e32 v67, v67
	v_exp_f32_e32 v68, v68
	v_add_f32_e32 v145, 0, v64
	v_exp_f32_e32 v69, v69
	v_add_f32_e32 v145, v65, v145
	v_exp_f32_e32 v70, v70
	v_add_f32_e32 v145, v66, v145
	v_exp_f32_e32 v71, v71
	v_add_f32_e32 v145, v67, v145
	v_exp_f32_e32 v72, v72
	v_add_f32_e32 v145, v68, v145
	v_exp_f32_e32 v73, v73
	v_add_f32_e32 v145, v69, v145
	v_exp_f32_e32 v74, v74
	v_add_f32_e32 v145, v70, v145
	v_exp_f32_e32 v75, v75
	v_add_f32_e32 v145, v71, v145
	v_exp_f32_e32 v76, v76
	v_add_f32_e32 v145, v72, v145
	v_exp_f32_e32 v77, v77
	v_add_f32_e32 v145, v73, v145
	v_exp_f32_e32 v78, v78
	v_add_f32_e32 v145, v74, v145
	v_exp_f32_e32 v79, v79
	v_add_f32_e32 v145, v75, v145
	v_add_f32_e32 v145, v76, v145
	v_add_f32_e32 v145, v77, v145
	v_add_f32_e32 v145, v78, v145
	v_add_f32_e32 v145, v79, v145
	v_add_f32_e32 v145, v173, v145
	v_cvt_pk_bf16_f32 v64, v64, v65
	v_cvt_pk_bf16_f32 v65, v66, v67
	v_cvt_pk_bf16_f32 v66, v68, v69
	v_cvt_pk_bf16_f32 v67, v70, v71
	v_cvt_pk_bf16_f32 v68, v72, v73
	v_cvt_pk_bf16_f32 v69, v74, v75
	v_cvt_pk_bf16_f32 v70, v76, v77
	v_cvt_pk_bf16_f32 v71, v78, v79
	s_nop 0
	v_permlane32_swap_b32_e32 v64, v66
	v_permlane32_swap_b32_e32 v65, v67
	v_permlane32_swap_b32_e32 v68, v70
	v_permlane32_swap_b32_e32 v69, v71
	s_waitcnt lgkmcnt(0)
	ds_read_b128 v[218:221], v167 offset:36864
	ds_read_b128 v[222:225], v168 offset:36864
	ds_read_b128 v[226:229], v169 offset:36864
	ds_read_b128 v[230:233], v170 offset:36864
	ds_read_b128 v[234:237], v171 offset:36864
	ds_read_b128 v[238:241], v172 offset:36864
	s_setprio 1
	v_mfma_f32_32x32x16_bf16 v[48:63], v[64:67], v[186:189], v[48:63]
	v_mfma_f32_32x32x16_bf16 v[32:47], v[64:67], v[194:197], v[32:47]
	v_mfma_f32_32x32x16_bf16 v[16:31], v[64:67], v[202:205], v[16:31]
	v_mfma_f32_32x32x16_bf16 v[0:15], v[64:67], v[210:213], v[0:15]
	v_mfma_f32_32x32x16_bf16 v[48:63], v[68:71], v[190:193], v[48:63]
	v_mfma_f32_32x32x16_bf16 v[32:47], v[68:71], v[198:201], v[32:47]
	v_mfma_f32_32x32x16_bf16 v[16:31], v[68:71], v[206:209], v[16:31]
	v_mfma_f32_32x32x16_bf16 v[0:15], v[68:71], v[214:217], v[0:15]
	s_waitcnt lgkmcnt(0)
; #define LAS __attribute__((address_space(3)))
; DI void expsum(f32x16& p, float& l_reg, bf16x8& pa0, bf16x8& pa1) {
; #pragma unroll
;     for (int r = 0; r < 16; ++r) p[r] = __builtin_amdgcn_exp2f(p[r]);
;     float ps = 0.f;
; #pragma unroll
;     for (int r = 0; r < 16; ++r) ps += p[r];
;     l_reg += ps; asm volatile("" : "+v"(l_reg));
;     ...
;     ATT_PK4(p, 0, pa0); ATT_PK4(p, 8, pa1);
;     ...
; }
; DI int v_rd_base(int lane) { return ((lane & 3) << 3) | (((lane >> 2) & 3) << 6) | (((lane >> 4) & 1) << 5) | (((lane >> 5) & 1) << 8); }
; template <int OFF> DI s16x4 tr_read(int vb) { s16x4 r; asm volatile("ds_read_b64_tr_b16 %0, %1 offset:%2" : "=&v"(r) : "v"(vb), "i"(OFF) : "memory"); return r; }
; template <int H> DI void v_reads(s16x4* vf, int vb) {
;     vf[0] = tr_read<v_rd_off(0, 2 * H, 0)>(vb); vf[1] = tr_read<v_rd_off(0, 2 * H, 1)>(vb); vf[2] = tr_read<v_rd_off(0, 2 * H + 1, 0)>(vb); vf[3] = tr_read<v_rd_off(0, 2 * H + 1, 1)>(vb);
;     vf[4] = tr_read<v_rd_off(1, 2 * H, 0)>(vb); vf[5] = tr_read<v_rd_off(1, 2 * H, 1)>(vb); vf[6] = tr_read<v_rd_off(1, 2 * H + 1, 0)>(vb); vf[7] = tr_read<v_rd_off(1, 2 * H + 1, 1)>(vb);
;     vf[8] = tr_read<v_rd_off(2, 2 * H, 0)>(vb); vf[9] = tr_read<v_rd_off(2, 2 * H, 1)>(vb); vf[10] = tr_read<v_rd_off(2, 2 * H + 1, 0)>(vb); vf[11] = tr_read<v_rd_off(2, 2 * H + 1, 1)>(vb);
;     vf[12] = tr_read<v_rd_off(3, 2 * H, 0)>(vb); vf[13] = tr_read<v_rd_off(3, 2 * H, 1)>(vb); vf[14] = tr_read<v_rd_off(3, 2 * H + 1, 0)>(vb); vf[15] = tr_read<v_rd_off(3, 2 * H + 1, 1)>(vb);
; }
; DI void pv_mma(f32x16* o, const s16x4* vf, bf16x8 pa0, bf16x8 pa1) {
;     ...
; #pragma unroll
;     for (int d0 = 0; d0 < 4; ++d0) {
;         o[d0] = __builtin_amdgcn_mfma_f32_32x32x16_bf16(pa0, ATT_PK(vf[4 * d0], vf[4 * d0 + 1]), o[d0], 0, 0, 0);
;         o[d0] = __builtin_amdgcn_mfma_f32_32x32x16_bf16(pa1, ATT_PK(vf[4 * d0 + 2], vf[4 * d0 + 3]), o[d0], 0, 0, 0); }
;     ...
; }
; template <int DQK, int D0A, int D0B> DI void k_reads(bf16x8* kf, const LAS unsigned char* Ks, int half, int r32, int hi) {
; #pragma unroll
;     for (int d0 = D0A; d0 < D0B; ++d0) kf[d0 - D0A] = *(const LAS bf16x8*)(Ks + half * (32 * DQK * 2) + kswz<DQK>(r32, (d0 * 16 + hi * 8) * 2));
; }
; template <int D0A, int D0B> DI void qk_mma(f32x16& p, const bf16x8* kf, const bf16x8* qr) {
; #pragma unroll
;     for (int d0 = D0A; d0 < D0B; ++d0) {
	v_mfma_f32_32x32x16_bf16 v[64:79], v[132:135], v[80:83], 0
	v_mfma_f32_32x32x16_bf16 v[64:79], v[136:139], v[84:87], v[64:79]
	v_mfma_f32_32x32x16_bf16 v[64:79], v[140:143], v[88:91], v[64:79]
	v_mfma_f32_32x32x16_bf16 v[64:79], v[174:177], v[92:95], v[64:79]
	v_mfma_f32_32x32x16_bf16 v[64:79], v[178:181], v[96:99], v[64:79]
	v_mfma_f32_32x32x16_bf16 v[64:79], v[182:185], v[100:103], v[64:79]
	s_waitcnt lgkmcnt(0)
	v_mfma_f32_32x32x16_bf16 v[64:79], v[218:221], v[104:107], v[64:79]
	v_mfma_f32_32x32x16_bf16 v[64:79], v[222:225], v[108:111], v[64:79]
	v_mfma_f32_32x32x16_bf16 v[64:79], v[226:229], v[112:115], v[64:79]
	v_mfma_f32_32x32x16_bf16 v[64:79], v[230:233], v[116:119], v[64:79]
	v_mfma_f32_32x32x16_bf16 v[64:79], v[234:237], v[120:123], v[64:79]
	v_mfma_f32_32x32x16_bf16 v[64:79], v[238:241], v[124:127], v[64:79]
	s_setprio 0
	ds_read_b128 v[132:135], v161 offset:49152
	ds_read_b128 v[136:139], v162 offset:49152
	ds_read_b128 v[140:143], v163 offset:49152
	ds_read_b128 v[174:177], v164 offset:49152
	ds_read_b128 v[178:181], v165 offset:49152
	ds_read_b128 v[182:185], v166 offset:49152
	ds_read_b64_tr_b16 v[186:187], v144 offset:0x2000
	ds_read_b64_tr_b16 v[188:189], v144 offset:0x2800
	ds_read_b64_tr_b16 v[190:191], v144 offset:0x3000
	ds_read_b64_tr_b16 v[192:193], v144 offset:0x3800
	ds_read_b64_tr_b16 v[194:195], v144 offset:0x2200
	ds_read_b64_tr_b16 v[196:197], v144 offset:0x2a00
	ds_read_b64_tr_b16 v[198:199], v144 offset:0x3200
	ds_read_b64_tr_b16 v[200:201], v144 offset:0x3a00
	ds_read_b64_tr_b16 v[202:203], v144 offset:0x2400
	ds_read_b64_tr_b16 v[204:205], v144 offset:0x2c00
	ds_read_b64_tr_b16 v[206:207], v144 offset:0x3400
	ds_read_b64_tr_b16 v[208:209], v144 offset:0x3c00
	ds_read_b64_tr_b16 v[210:211], v144 offset:0x2600
	ds_read_b64_tr_b16 v[212:213], v144 offset:0x2e00
	ds_read_b64_tr_b16 v[214:215], v144 offset:0x3600
	ds_read_b64_tr_b16 v[216:217], v144 offset:0x3e00
	s_nop 5
	s_setprio 2
	v_exp_f32_e32 v64, v64
	v_exp_f32_e32 v65, v65
	v_exp_f32_e32 v66, v66
	v_exp_f32_e32 v67, v67
	v_exp_f32_e32 v68, v68
	v_add_f32_e32 v144, 0, v64
	v_exp_f32_e32 v69, v69
	v_add_f32_e32 v144, v65, v144
	v_exp_f32_e32 v70, v70
	v_add_f32_e32 v144, v66, v144
	v_exp_f32_e32 v71, v71
	v_add_f32_e32 v144, v67, v144
	v_exp_f32_e32 v72, v72
	v_add_f32_e32 v144, v68, v144
	v_exp_f32_e32 v73, v73
	v_add_f32_e32 v144, v69, v144
	v_exp_f32_e32 v74, v74
	v_add_f32_e32 v144, v70, v144
	v_exp_f32_e32 v75, v75
	v_add_f32_e32 v144, v71, v144
	v_exp_f32_e32 v76, v76
	v_add_f32_e32 v144, v72, v144
	v_exp_f32_e32 v77, v77
	v_add_f32_e32 v144, v73, v144
	v_exp_f32_e32 v78, v78
	v_add_f32_e32 v144, v74, v144
	v_exp_f32_e32 v79, v79
	v_add_f32_e32 v144, v75, v144
	v_add_f32_e32 v144, v76, v144
	v_add_f32_e32 v144, v77, v144
	v_add_f32_e32 v144, v78, v144
	v_add_f32_e32 v144, v79, v144
	v_add_f32_e32 v144, v145, v144
	v_cvt_pk_bf16_f32 v64, v64, v65
	v_cvt_pk_bf16_f32 v65, v66, v67
	v_cvt_pk_bf16_f32 v66, v68, v69
	v_cvt_pk_bf16_f32 v67, v70, v71
	v_cvt_pk_bf16_f32 v68, v72, v73
	v_cvt_pk_bf16_f32 v69, v74, v75
	v_cvt_pk_bf16_f32 v70, v76, v77
	v_cvt_pk_bf16_f32 v71, v78, v79
	s_nop 0
	v_permlane32_swap_b32_e32 v64, v66
	v_permlane32_swap_b32_e32 v65, v67
	v_permlane32_swap_b32_e32 v68, v70
	v_permlane32_swap_b32_e32 v69, v71
	s_waitcnt lgkmcnt(0)
	ds_read_b128 v[218:221], v167 offset:49152
	ds_read_b128 v[222:225], v168 offset:49152
	ds_read_b128 v[226:229], v169 offset:49152
	ds_read_b128 v[230:233], v170 offset:49152
	ds_read_b128 v[234:237], v171 offset:49152
	ds_read_b128 v[238:241], v172 offset:49152
	s_setprio 1
	s_cmp_ge_u32 s33, 0x100
	s_cbranch_scc1 .Lstg_mla_m61_5
	s_waitcnt vmcnt(0)
	s_barrier
.Lstg_mla_m61_5:
	v_mfma_f32_32x32x16_bf16 v[48:63], v[64:67], v[186:189], v[48:63]
	v_mfma_f32_32x32x16_bf16 v[32:47], v[64:67], v[194:197], v[32:47]
	v_mfma_f32_32x32x16_bf16 v[16:31], v[64:67], v[202:205], v[16:31]
	v_mfma_f32_32x32x16_bf16 v[0:15], v[64:67], v[210:213], v[0:15]
	v_mfma_f32_32x32x16_bf16 v[48:63], v[68:71], v[190:193], v[48:63]
	v_mfma_f32_32x32x16_bf16 v[32:47], v[68:71], v[198:201], v[32:47]
	v_mfma_f32_32x32x16_bf16 v[16:31], v[68:71], v[206:209], v[16:31]
	v_mfma_f32_32x32x16_bf16 v[0:15], v[68:71], v[214:217], v[0:15]
	s_waitcnt lgkmcnt(0)
	v_mfma_f32_32x32x16_bf16 v[64:79], v[132:135], v[80:83], 0
	v_mfma_f32_32x32x16_bf16 v[64:79], v[136:139], v[84:87], v[64:79]
	v_mfma_f32_32x32x16_bf16 v[64:79], v[140:143], v[88:91], v[64:79]
	v_mfma_f32_32x32x16_bf16 v[64:79], v[174:177], v[92:95], v[64:79]
	v_mfma_f32_32x32x16_bf16 v[64:79], v[178:181], v[96:99], v[64:79]
	v_mfma_f32_32x32x16_bf16 v[64:79], v[182:185], v[100:103], v[64:79]
	s_waitcnt lgkmcnt(0)
	v_mfma_f32_32x32x16_bf16 v[64:79], v[218:221], v[104:107], v[64:79]
	v_mfma_f32_32x32x16_bf16 v[64:79], v[222:225], v[108:111], v[64:79]
	v_mfma_f32_32x32x16_bf16 v[64:79], v[226:229], v[112:115], v[64:79]
	v_mfma_f32_32x32x16_bf16 v[64:79], v[230:233], v[116:119], v[64:79]
	v_mfma_f32_32x32x16_bf16 v[64:79], v[234:237], v[120:123], v[64:79]
	v_mfma_f32_32x32x16_bf16 v[64:79], v[238:241], v[124:127], v[64:79]
	s_cmp_ge_u32 s33, 0x100
	s_cbranch_scc0 .Lstg_mla_t62_6
	s_waitcnt vmcnt(0)
	s_barrier
; #define LAS __attribute__((address_space(3)))
; DI void expsum(f32x16& p, float& l_reg, bf16x8& pa0, bf16x8& pa1) {
; #pragma unroll
;     for (int r = 0; r < 16; ++r) p[r] = __builtin_amdgcn_exp2f(p[r]);
;     float ps = 0.f;
; #pragma unroll
;     for (int r = 0; r < 16; ++r) ps += p[r];
;     l_reg += ps; asm volatile("" : "+v"(l_reg));
;     ...
;     ATT_PK4(p, 0, pa0); ATT_PK4(p, 8, pa1);
;     ...
; }
; DI int v_rd_base(int lane) { return ((lane & 3) << 3) | (((lane >> 2) & 3) << 6) | (((lane >> 4) & 1) << 5) | (((lane >> 5) & 1) << 8); }
; template <int OFF> DI s16x4 tr_read(int vb) { s16x4 r; asm volatile("ds_read_b64_tr_b16 %0, %1 offset:%2" : "=&v"(r) : "v"(vb), "i"(OFF) : "memory"); return r; }
; template <int H> DI void v_reads(s16x4* vf, int vb) {
;     vf[0] = tr_read<v_rd_off(0, 2 * H, 0)>(vb); vf[1] = tr_read<v_rd_off(0, 2 * H, 1)>(vb); vf[2] = tr_read<v_rd_off(0, 2 * H + 1, 0)>(vb); vf[3] = tr_read<v_rd_off(0, 2 * H + 1, 1)>(vb);
;     vf[4] = tr_read<v_rd_off(1, 2 * H, 0)>(vb); vf[5] = tr_read<v_rd_off(1, 2 * H, 1)>(vb); vf[6] = tr_read<v_rd_off(1, 2 * H + 1, 0)>(vb); vf[7] = tr_read<v_rd_off(1, 2 * H + 1, 1)>(vb);
;     vf[8] = tr_read<v_rd_off(2, 2 * H, 0)>(vb); vf[9] = tr_read<v_rd_off(2, 2 * H, 1)>(vb); vf[10] = tr_read<v_rd_off(2, 2 * H + 1, 0)>(vb); vf[11] = tr_read<v_rd_off(2, 2 * H + 1, 1)>(vb);
;     vf[12] = tr_read<v_rd_off(3, 2 * H, 0)>(vb); vf[13] = tr_read<v_rd_off(3, 2 * H, 1)>(vb); vf[14] = tr_read<v_rd_off(3, 2 * H + 1, 0)>(vb); vf[15] = tr_read<v_rd_off(3, 2 * H + 1, 1)>(vb);
; }
; DI void pv_mma(f32x16* o, const s16x4* vf, bf16x8 pa0, bf16x8 pa1) {
;     ...
; #pragma unroll
;     for (int d0 = 0; d0 < 4; ++d0) {
;         o[d0] = __builtin_amdgcn_mfma_f32_32x32x16_bf16(pa0, ATT_PK(vf[4 * d0], vf[4 * d0 + 1]), o[d0], 0, 0, 0);
;         o[d0] = __builtin_amdgcn_mfma_f32_32x32x16_bf16(pa1, ATT_PK(vf[4 * d0 + 2], vf[4 * d0 + 3]), o[d0], 0, 0, 0); }
;     ...
; }
; template <int DQK, int D0A, int D0B> DI void k_reads(bf16x8* kf, const LAS unsigned char* Ks, int half, int r32, int hi) {
; #pragma unroll
;     for (int d0 = D0A; d0 < D0B; ++d0) kf[d0 - D0A] = *(const LAS bf16x8*)(Ks + half * (32 * DQK * 2) + kswz<DQK>(r32, (d0 * 16 + hi * 8) * 2));
; }
; template <int D0A, int D0B> DI void qk_mma(f32x16& p, const bf16x8* kf, const bf16x8* qr) {
; #pragma unroll
;     for (int d0 = D0A; d0 < D0B; ++d0) {
.Lstg_mla_t62_6:
	s_setprio 0
	ds_read_b128 v[132:135], v161 offset:61440
	ds_read_b128 v[136:139], v162 offset:61440
	ds_read_b128 v[140:143], v163 offset:61440
	ds_read_b128 v[174:177], v164 offset:61440
	ds_read_b128 v[162:165], v165 offset:61440
	ds_read_b128 v[178:181], v166 offset:61440
	v_add_u32_e32 v145, 0x8000, v130
	ds_read_b64_tr_b16 v[182:183], v145 offset:0
	ds_read_b64_tr_b16 v[184:185], v145 offset:0x800
	ds_read_b64_tr_b16 v[186:187], v145 offset:0x1000
	ds_read_b64_tr_b16 v[188:189], v145 offset:0x1800
	ds_read_b64_tr_b16 v[190:191], v145 offset:0x200
	ds_read_b64_tr_b16 v[192:193], v145 offset:0xa00
	ds_read_b64_tr_b16 v[194:195], v145 offset:0x1200
	ds_read_b64_tr_b16 v[196:197], v145 offset:0x1a00
	ds_read_b64_tr_b16 v[198:199], v145 offset:0x400
	ds_read_b64_tr_b16 v[200:201], v145 offset:0xc00
	ds_read_b64_tr_b16 v[202:203], v145 offset:0x1400
	ds_read_b64_tr_b16 v[204:205], v145 offset:0x1c00
	ds_read_b64_tr_b16 v[206:207], v145 offset:0x600
	ds_read_b64_tr_b16 v[208:209], v145 offset:0xe00
	ds_read_b64_tr_b16 v[210:211], v145 offset:0x1600
	ds_read_b64_tr_b16 v[212:213], v145 offset:0x1e00
	s_nop 3
	s_setprio 2
	v_exp_f32_e32 v64, v64
	v_exp_f32_e32 v65, v65
	v_exp_f32_e32 v66, v66
	v_exp_f32_e32 v67, v67
	v_exp_f32_e32 v68, v68
	v_add_f32_e32 v161, 0, v64
	v_exp_f32_e32 v69, v69
	v_add_f32_e32 v161, v65, v161
	v_exp_f32_e32 v70, v70
	v_add_f32_e32 v161, v66, v161
	v_exp_f32_e32 v71, v71
	v_add_f32_e32 v161, v67, v161
	v_exp_f32_e32 v72, v72
	v_add_f32_e32 v161, v68, v161
	v_exp_f32_e32 v73, v73
	v_add_f32_e32 v161, v69, v161
	v_exp_f32_e32 v74, v74
	v_add_f32_e32 v161, v70, v161
	v_exp_f32_e32 v75, v75
	v_add_f32_e32 v161, v71, v161
	v_exp_f32_e32 v76, v76
	v_add_f32_e32 v161, v72, v161
	v_exp_f32_e32 v77, v77
	v_add_f32_e32 v161, v73, v161
	v_exp_f32_e32 v78, v78
	v_add_f32_e32 v161, v74, v161
	v_exp_f32_e32 v79, v79
	v_add_f32_e32 v161, v75, v161
	v_add_f32_e32 v161, v76, v161
	v_add_f32_e32 v161, v77, v161
	v_add_f32_e32 v161, v78, v161
	v_add_f32_e32 v161, v79, v161
	v_add_f32_e32 v144, v144, v161
	v_cvt_pk_bf16_f32 v64, v64, v65
	v_cvt_pk_bf16_f32 v65, v66, v67
	v_cvt_pk_bf16_f32 v66, v68, v69
	v_cvt_pk_bf16_f32 v67, v70, v71
	v_cvt_pk_bf16_f32 v68, v72, v73
	v_cvt_pk_bf16_f32 v69, v74, v75
	v_cvt_pk_bf16_f32 v70, v76, v77
	v_cvt_pk_bf16_f32 v71, v78, v79
	s_nop 0
	v_permlane32_swap_b32_e32 v64, v66
	v_permlane32_swap_b32_e32 v65, v67
	v_permlane32_swap_b32_e32 v68, v70
	v_permlane32_swap_b32_e32 v69, v71
	s_waitcnt lgkmcnt(0)
	ds_read_b128 v[214:217], v167 offset:61440
	ds_read_b128 v[218:221], v168 offset:61440
	ds_read_b128 v[166:169], v169 offset:61440
	ds_read_b128 v[222:225], v170 offset:61440
	ds_read_b128 v[226:229], v171 offset:61440
	ds_read_b128 v[170:173], v172 offset:61440
	s_setprio 1
	v_mfma_f32_32x32x16_bf16 v[48:63], v[64:67], v[182:185], v[48:63]
	v_mfma_f32_32x32x16_bf16 v[32:47], v[64:67], v[190:193], v[32:47]
	v_mfma_f32_32x32x16_bf16 v[16:31], v[64:67], v[198:201], v[16:31]
	v_mfma_f32_32x32x16_bf16 v[0:15], v[64:67], v[206:209], v[0:15]
	v_mfma_f32_32x32x16_bf16 v[48:63], v[68:71], v[186:189], v[48:63]
	v_mfma_f32_32x32x16_bf16 v[32:47], v[68:71], v[194:197], v[32:47]
	v_mfma_f32_32x32x16_bf16 v[16:31], v[68:71], v[202:205], v[16:31]
	v_mfma_f32_32x32x16_bf16 v[0:15], v[68:71], v[210:213], v[0:15]
	s_waitcnt lgkmcnt(0)
	v_mfma_f32_32x32x16_bf16 v[64:79], v[132:135], v[80:83], 0
	v_mfma_f32_32x32x16_bf16 v[64:79], v[136:139], v[84:87], v[64:79]
	v_mfma_f32_32x32x16_bf16 v[64:79], v[140:143], v[88:91], v[64:79]
	v_mfma_f32_32x32x16_bf16 v[64:79], v[174:177], v[92:95], v[64:79]
	v_mfma_f32_32x32x16_bf16 v[64:79], v[162:165], v[96:99], v[64:79]
	v_mfma_f32_32x32x16_bf16 v[64:79], v[178:181], v[100:103], v[64:79]
	s_waitcnt lgkmcnt(0)
; #define LAS __attribute__((address_space(3)))
; DI void expsum(f32x16& p, float& l_reg, bf16x8& pa0, bf16x8& pa1) {
; #pragma unroll
;     for (int r = 0; r < 16; ++r) p[r] = __builtin_amdgcn_exp2f(p[r]);
;     float ps = 0.f;
; #pragma unroll
;     for (int r = 0; r < 16; ++r) ps += p[r];
;     l_reg += ps; asm volatile("" : "+v"(l_reg));
;     ...
;     ATT_PK4(p, 0, pa0); ATT_PK4(p, 8, pa1);
;     ...
; }
; DI int v_rd_base(int lane) { return ((lane & 3) << 3) | (((lane >> 2) & 3) << 6) | (((lane >> 4) & 1) << 5) | (((lane >> 5) & 1) << 8); }
; template <int OFF> DI s16x4 tr_read(int vb) { s16x4 r; asm volatile("ds_read_b64_tr_b16 %0, %1 offset:%2" : "=&v"(r) : "v"(vb), "i"(OFF) : "memory"); return r; }
; template <int H> DI void v_reads(s16x4* vf, int vb) {
;     vf[0] = tr_read<v_rd_off(0, 2 * H, 0)>(vb); vf[1] = tr_read<v_rd_off(0, 2 * H, 1)>(vb); vf[2] = tr_read<v_rd_off(0, 2 * H + 1, 0)>(vb); vf[3] = tr_read<v_rd_off(0, 2 * H + 1, 1)>(vb);
;     vf[4] = tr_read<v_rd_off(1, 2 * H, 0)>(vb); vf[5] = tr_read<v_rd_off(1, 2 * H, 1)>(vb); vf[6] = tr_read<v_rd_off(1, 2 * H + 1, 0)>(vb); vf[7] = tr_read<v_rd_off(1, 2 * H + 1, 1)>(vb);
;     vf[8] = tr_read<v_rd_off(2, 2 * H, 0)>(vb); vf[9] = tr_read<v_rd_off(2, 2 * H, 1)>(vb); vf[10] = tr_read<v_rd_off(2, 2 * H + 1, 0)>(vb); vf[11] = tr_read<v_rd_off(2, 2 * H + 1, 1)>(vb);
;     vf[12] = tr_read<v_rd_off(3, 2 * H, 0)>(vb); vf[13] = tr_read<v_rd_off(3, 2 * H, 1)>(vb); vf[14] = tr_read<v_rd_off(3, 2 * H + 1, 0)>(vb); vf[15] = tr_read<v_rd_off(3, 2 * H + 1, 1)>(vb);
; }
; DI void pv_mma(f32x16* o, const s16x4* vf, bf16x8 pa0, bf16x8 pa1) {
;     ...
; #pragma unroll
;     for (int d0 = 0; d0 < 4; ++d0) {
;         o[d0] = __builtin_amdgcn_mfma_f32_32x32x16_bf16(pa0, ATT_PK(vf[4 * d0], vf[4 * d0 + 1]), o[d0], 0, 0, 0);
;         o[d0] = __builtin_amdgcn_mfma_f32_32x32x16_bf16(pa1, ATT_PK(vf[4 * d0 + 2], vf[4 * d0 + 3]), o[d0], 0, 0, 0); }
;     ...
; }
; template <int DQK, int D0A, int D0B> DI void k_reads(bf16x8* kf, const LAS unsigned char* Ks, int half, int r32, int hi) {
; #pragma unroll
;     for (int d0 = D0A; d0 < D0B; ++d0) kf[d0 - D0A] = *(const LAS bf16x8*)(Ks + half * (32 * DQK * 2) + kswz<DQK>(r32, (d0 * 16 + hi * 8) * 2));
; }
; template <int D0A, int D0B> DI void qk_mma(f32x16& p, const bf16x8* kf, const bf16x8* qr) {
; #pragma unroll
;     for (int d0 = D0A; d0 < D0B; ++d0) {
	v_mfma_f32_32x32x16_bf16 v[64:79], v[214:217], v[104:107], v[64:79]
	v_mfma_f32_32x32x16_bf16 v[64:79], v[218:221], v[108:111], v[64:79]
	v_mfma_f32_32x32x16_bf16 v[64:79], v[166:169], v[112:115], v[64:79]
	v_mfma_f32_32x32x16_bf16 v[64:79], v[222:225], v[116:119], v[64:79]
	v_mfma_f32_32x32x16_bf16 v[64:79], v[226:229], v[120:123], v[64:79]
	v_mfma_f32_32x32x16_bf16 v[64:79], v[170:173], v[124:127], v[64:79]
	s_setprio 0
	v_add_u32_e32 v158, 0x12000, v158
	v_add_u32_e32 v132, v158, v151
	v_add_u32_e32 v136, v158, v149
	v_add_u32_e32 v140, v158, v148
	v_add_u32_e32 v161, v158, v147
	ds_read_b128 v[132:135], v132
	ds_read_b128 v[136:139], v136
	ds_read_b128 v[140:143], v140
	ds_read_b128 v[162:165], v161
	v_add_u32_e32 v161, v158, v146
	v_add_u32_e32 v170, v158, v150
	ds_read_b128 v[166:169], v161
	ds_read_b128 v[170:173], v170
	ds_read_b64_tr_b16 v[174:175], v145 offset:0x2000
	ds_read_b64_tr_b16 v[176:177], v145 offset:0x2800
	ds_read_b64_tr_b16 v[178:179], v145 offset:0x3000
	ds_read_b64_tr_b16 v[180:181], v145 offset:0x3800
	ds_read_b64_tr_b16 v[182:183], v145 offset:0x2200
	ds_read_b64_tr_b16 v[184:185], v145 offset:0x2a00
	ds_read_b64_tr_b16 v[186:187], v145 offset:0x3200
	ds_read_b64_tr_b16 v[188:189], v145 offset:0x3a00
	ds_read_b64_tr_b16 v[190:191], v145 offset:0x2400
	ds_read_b64_tr_b16 v[192:193], v145 offset:0x2c00
	ds_read_b64_tr_b16 v[194:195], v145 offset:0x3400
	ds_read_b64_tr_b16 v[196:197], v145 offset:0x3c00
	ds_read_b64_tr_b16 v[198:199], v145 offset:0x2600
	ds_read_b64_tr_b16 v[200:201], v145 offset:0x2e00
	ds_read_b64_tr_b16 v[202:203], v145 offset:0x3600
	ds_read_b64_tr_b16 v[204:205], v145 offset:0x3e00
	s_setprio 2
	v_exp_f32_e32 v64, v64
	v_exp_f32_e32 v65, v65
	v_exp_f32_e32 v66, v66
	v_exp_f32_e32 v67, v67
	v_exp_f32_e32 v68, v68
	v_add_f32_e32 v145, 0, v64
	v_exp_f32_e32 v69, v69
	v_add_f32_e32 v145, v65, v145
	v_exp_f32_e32 v70, v70
	v_add_f32_e32 v145, v66, v145
	v_exp_f32_e32 v71, v71
	v_add_f32_e32 v145, v67, v145
	v_exp_f32_e32 v72, v72
	v_add_f32_e32 v145, v68, v145
	v_exp_f32_e32 v73, v73
	v_add_f32_e32 v145, v69, v145
	v_exp_f32_e32 v74, v74
	v_add_f32_e32 v145, v70, v145
	v_exp_f32_e32 v75, v75
	v_add_f32_e32 v145, v71, v145
	v_exp_f32_e32 v76, v76
	v_add_f32_e32 v145, v72, v145
	v_exp_f32_e32 v77, v77
	v_add_f32_e32 v145, v73, v145
	v_exp_f32_e32 v78, v78
	v_add_f32_e32 v145, v74, v145
	v_exp_f32_e32 v79, v79
	v_add_f32_e32 v145, v75, v145
	v_add_f32_e32 v145, v76, v145
	v_add_f32_e32 v145, v77, v145
	v_add_f32_e32 v145, v78, v145
	v_add_f32_e32 v145, v79, v145
	v_add_f32_e32 v161, v144, v145
	v_cvt_pk_bf16_f32 v64, v64, v65
	v_cvt_pk_bf16_f32 v65, v66, v67
	v_cvt_pk_bf16_f32 v66, v68, v69
	v_cvt_pk_bf16_f32 v67, v70, v71
	v_cvt_pk_bf16_f32 v68, v72, v73
	v_cvt_pk_bf16_f32 v69, v74, v75
	v_cvt_pk_bf16_f32 v70, v76, v77
	v_cvt_pk_bf16_f32 v71, v78, v79
	s_nop 0
	v_permlane32_swap_b32_e32 v64, v66
	v_permlane32_swap_b32_e32 v65, v67
	v_permlane32_swap_b32_e32 v68, v70
	v_permlane32_swap_b32_e32 v69, v71
	s_waitcnt lgkmcnt(0)
	v_add_u32_e32 v72, v158, v152
	v_add_u32_e32 v73, v158, v153
	ds_read_b128 v[206:209], v72
	ds_read_b128 v[210:213], v73
	v_add_u32_e32 v72, v158, v154
	v_add_u32_e32 v73, v158, v155
	ds_read_b128 v[214:217], v72
	ds_read_b128 v[218:221], v73
	v_add_u32_e32 v72, v158, v156
	v_add_u32_e32 v73, v158, v157
	ds_read_b128 v[222:225], v72
	ds_read_b128 v[226:229], v73
	s_setprio 1
	s_cmp_ge_u32 s33, 0x100
	s_cbranch_scc1 .Lstg_mla_m62_7
	s_waitcnt vmcnt(0)
	s_barrier
.Lstg_mla_m62_7:
	v_mfma_f32_32x32x16_bf16 v[48:63], v[64:67], v[174:177], v[48:63]
	v_mfma_f32_32x32x16_bf16 v[32:47], v[64:67], v[182:185], v[32:47]
	v_mfma_f32_32x32x16_bf16 v[16:31], v[64:67], v[190:193], v[16:31]
	v_mfma_f32_32x32x16_bf16 v[0:15], v[64:67], v[198:201], v[0:15]
	v_mfma_f32_32x32x16_bf16 v[48:63], v[68:71], v[178:181], v[48:63]
	v_mfma_f32_32x32x16_bf16 v[32:47], v[68:71], v[186:189], v[32:47]
	v_mfma_f32_32x32x16_bf16 v[16:31], v[68:71], v[194:197], v[16:31]
	v_mfma_f32_32x32x16_bf16 v[0:15], v[68:71], v[202:205], v[0:15]
	s_waitcnt lgkmcnt(0)
	v_mfma_f32_32x32x16_bf16 v[64:79], v[132:135], v[80:83], 0
	v_mfma_f32_32x32x16_bf16 v[64:79], v[136:139], v[84:87], v[64:79]
	v_mfma_f32_32x32x16_bf16 v[64:79], v[140:143], v[88:91], v[64:79]
	v_mfma_f32_32x32x16_bf16 v[64:79], v[162:165], v[92:95], v[64:79]
	v_mfma_f32_32x32x16_bf16 v[64:79], v[166:169], v[96:99], v[64:79]
	v_mfma_f32_32x32x16_bf16 v[64:79], v[170:173], v[100:103], v[64:79]
	s_waitcnt lgkmcnt(0)
	v_mfma_f32_32x32x16_bf16 v[64:79], v[206:209], v[104:107], v[64:79]
	v_mfma_f32_32x32x16_bf16 v[64:79], v[210:213], v[108:111], v[64:79]
	v_mfma_f32_32x32x16_bf16 v[64:79], v[214:217], v[112:115], v[64:79]
	v_mfma_f32_32x32x16_bf16 v[64:79], v[218:221], v[116:119], v[64:79]
	v_mfma_f32_32x32x16_bf16 v[64:79], v[222:225], v[120:123], v[64:79]
	v_mfma_f32_32x32x16_bf16 v[64:79], v[226:229], v[124:127], v[64:79]
	s_cmp_ge_u32 s33, 0x100
	s_cbranch_scc0 .Lstg_mla_t63_8
	s_waitcnt vmcnt(0)
	s_barrier
